# c8 plus blocked 16x32 layout for the gate sections (sig ratio -> merged, sig gB): W_in gate-tile stores, G3/G4 mid+final epilogue loads/stores and the w_o GEMM A-operand loads become contiguous full c
# speedup vs baseline: 1.0247x; 1.0100x over previous
; __device__ __forceinline__ unsigned cvt_pk_bf16(float lo, float hi) { unsigned r; asm volatile("v_cvt_pk_bf16_f32 %0, %1, %2" : "=v"(r) : "v"(lo), "v"(hi)); return r; }
;     __device__ __forceinline__ void operator()(const AccT& acc, const Unit& u, int wr, int wc, int fr, int fq) const {
;     ...
;         if (u.pn >= 40) {
;             const int ch0 = (u.pn - 40) * 128 + wc * 32 + 8 * fq;
;             f32x4 ba[2], bb[2];
; #pragma unroll
;             for (int n = 0; n < 2; ++n) { ba[n] = *(const f32x4*)(bias + 5 * D + ch0 + 4 * n); bb[n] = *(const f32x4*)(bias + 6 * D + ch0 + 4 * n); }
; #pragma unroll
;             for (int ai = 0; ai < 2; ++ai)
; #pragma unroll
;                 for (int m = 0; m < 4; ++m) { const int row = row0 + ai * 128 + m * 16;
;                     const float rstd = rs[ai * 4 + m];
;                     f32x4 rt[2], sb[2];
; #pragma unroll
;                     for (int n = 0; n < 2; ++n)
; #pragma unroll
;                         for (int j = 0; j < 4; ++j) { const float ea = __builtin_amdgcn_exp2f(-LOG2E * (acc[ai][0][m][n][j] * rstd + ba[n][j])), eb = __builtin_amdgcn_exp2f(-LOG2E * (acc[ai][1][m][n][j] * rstd + bb[n][j]));
;                             sb[n][j] = __builtin_amdgcn_rcpf(1.0f + eb); rt[n][j] = (1.0f + eb) * __builtin_amdgcn_rcpf(1.0f + ea); }
;                     u32x4 w; w.x = cvt_pk_bf16(rt[0][0], rt[0][1]); w.y = cvt_pk_bf16(rt[0][2], rt[0][3]); w.z = cvt_pk_bf16(rt[1][0], rt[1][1]); w.w = cvt_pk_bf16(rt[1][2], rt[1][3]);
;                     *(u32x4*)(Z + 5 * SEC + (size_t)row * D + ch0) = w;
;                     u32x4 v; v.x = cvt_pk_bf16(sb[0][0], sb[0][1]); v.y = cvt_pk_bf16(sb[0][2], sb[0][3]); v.z = cvt_pk_bf16(sb[1][0], sb[1][1]); v.w = cvt_pk_bf16(sb[1][2], sb[1][3]);
;                     *(u32x4*)(Z + 6 * SEC + (size_t)row * D + ch0) = v; }
;             return;
.LBB0_125:
	s_andn2_b64 vcc, exec, s[16:17]
	s_cbranch_vccnz .LBB0_127
	v_lshl_add_u32 v0, s88, 7, v175
	v_lshlrev_b64 v[130:131], 2, v[0:1]
	v_lshl_add_u64 v[134:135], s[10:11], 0, v[130:131]
	v_lshl_add_u64 v[138:139], s[12:13], 0, v[130:131]
	global_load_dwordx4 v[130:133], v[134:135], off offset:16
	global_load_dwordx4 v[142:145], v[134:135], off
	s_nop 0
	global_load_dwordx4 v[134:137], v[138:139], off offset:16
	s_nop 0
	global_load_dwordx4 v[138:141], v[138:139], off
	s_mov_b64 s[16:17], 0x80000
	s_waitcnt vmcnt(0) lgkmcnt(0)
	v_fma_f32 v165, v126, v166, v142
	v_mul_f32_e32 v165, 0xbfb8aa3b, v165
	v_exp_f32_e32 v165, v165
	v_fma_f32 v168, v118, v166, v138
	v_mul_f32_e32 v168, 0xbfb8aa3b, v168
	v_exp_f32_e32 v168, v168
	v_add_f32_e32 v165, 1.0, v165
	v_rcp_f32_e32 v165, v165
	v_fma_f32 v169, v119, v166, v139
	v_add_f32_e32 v168, 1.0, v168
	v_rcp_f32_e32 v182, v168
	v_mul_f32_e32 v165, v165, v168
	v_fma_f32 v168, v127, v166, v143
	v_mul_f32_e32 v168, 0xbfb8aa3b, v168
	v_exp_f32_e32 v168, v168
	v_mul_f32_e32 v169, 0xbfb8aa3b, v169
	v_exp_f32_e32 v169, v169
	v_fma_f32 v170, v120, v166, v140
	v_add_f32_e32 v168, 1.0, v168
	v_rcp_f32_e32 v168, v168
	v_add_f32_e32 v169, 1.0, v169
	v_rcp_f32_e32 v183, v169
	v_mul_f32_e32 v170, 0xbfb8aa3b, v170
	v_mul_f32_e32 v168, v168, v169
	v_fma_f32 v169, v128, v166, v144
	v_mul_f32_e32 v169, 0xbfb8aa3b, v169
	v_exp_f32_e32 v169, v169
	v_exp_f32_e32 v170, v170
	v_fma_f32 v171, v121, v166, v141
	v_mul_f32_e32 v171, 0xbfb8aa3b, v171
	v_add_f32_e32 v169, 1.0, v169
	v_rcp_f32_e32 v169, v169
	v_add_f32_e32 v170, 1.0, v170
	v_rcp_f32_e32 v184, v170
	v_exp_f32_e32 v171, v171
	v_mul_f32_e32 v169, v169, v170
	v_fma_f32 v170, v129, v166, v145
	v_mul_f32_e32 v170, 0xbfb8aa3b, v170
	v_exp_f32_e32 v170, v170
	v_add_f32_e32 v171, 1.0, v171
	v_rcp_f32_e32 v185, v171
	v_fma_f32 v186, v114, v166, v134
	v_add_f32_e32 v170, 1.0, v170
	v_rcp_f32_e32 v170, v170
	v_mul_f32_e32 v186, 0xbfb8aa3b, v186
	v_exp_f32_e32 v186, v186
	v_fma_f32 v187, v115, v166, v135
	v_mul_f32_e32 v170, v170, v171
	v_fma_f32 v171, v122, v166, v130
	v_mul_f32_e32 v171, 0xbfb8aa3b, v171
	v_exp_f32_e32 v171, v171
	v_add_f32_e32 v186, 1.0, v186
	v_rcp_f32_e32 v192, v186
	v_mul_f32_e32 v187, 0xbfb8aa3b, v187
	v_add_f32_e32 v171, 1.0, v171
	v_rcp_f32_e32 v171, v171
	v_exp_f32_e32 v187, v187
	v_mul_f32_e32 v171, v171, v186
	v_fma_f32 v186, v123, v166, v131
	v_mul_f32_e32 v186, 0xbfb8aa3b, v186
	v_exp_f32_e32 v186, v186
	v_add_f32_e32 v187, 1.0, v187
	v_rcp_f32_e32 v193, v187
	v_add_f32_e32 v186, 1.0, v186
	v_rcp_f32_e32 v186, v186
	s_nop 0
	v_mul_f32_e32 v188, v186, v187
	v_fma_f32 v186, v124, v166, v132
	v_mul_f32_e32 v186, 0xbfb8aa3b, v186
	v_exp_f32_e32 v186, v186
	v_fma_f32 v187, v116, v166, v136
	v_mul_f32_e32 v187, 0xbfb8aa3b, v187
	v_exp_f32_e32 v187, v187
	v_add_f32_e32 v186, 1.0, v186
	v_rcp_f32_e32 v186, v186
	v_add_f32_e32 v187, 1.0, v187
	v_rcp_f32_e32 v194, v187
	v_mul_f32_e32 v189, v186, v187
	v_fma_f32 v186, v125, v166, v133
	v_mul_f32_e32 v186, 0xbfb8aa3b, v186
	v_exp_f32_e32 v186, v186
	v_fma_f32 v187, v117, v166, v137
	v_mul_f32_e32 v187, 0xbfb8aa3b, v187
	v_exp_f32_e32 v187, v187
	v_add_f32_e32 v186, 1.0, v186
	v_rcp_f32_e32 v186, v186
	v_add_f32_e32 v187, 1.0, v187
	v_rcp_f32_e32 v195, v187
	v_mul_f32_e32 v190, v186, v187
	v_cvt_pk_bf16_f32 v186, v165, v168
	v_cvt_pk_bf16_f32 v187, v169, v170
	v_lshrrev_b32_e32 v168, 5, v0
	v_lshlrev_b32_e32 v168, 10, v168
	v_and_b32_e32 v169, 31, v0
	v_lshl_add_u32 v168, v169, 1, v168
	v_and_b32_e32 v169, 15, v164
	v_lshl_add_u32 v168, v169, 6, v168
	v_mov_b32_e32 v169, 0
	v_fma_f32 v0, v110, v167, v142
	v_mul_f32_e32 v0, 0xbfb8aa3b, v0
	v_exp_f32_e32 v0, v0
	v_ashrrev_i32_e32 v165, 31, v164
	v_cvt_pk_bf16_f32 v188, v171, v188
	v_and_b32_e32 v170, 0xfffffff0, v164
	v_mov_b32_e32 v171, 0
	v_lshlrev_b64 v[170:171], 12, v[170:171]
	v_fma_f32 v165, v102, v167, v138
	v_mul_f32_e32 v165, 0xbfb8aa3b, v165
	v_exp_f32_e32 v165, v165
	v_add_f32_e32 v0, 1.0, v0
	v_rcp_f32_e32 v0, v0
	v_cvt_pk_bf16_f32 v189, v189, v190
	v_lshl_add_u64 v[190:191], s[14:15], 0, v[170:171]
	v_lshl_add_u64 v[190:191], v[190:191], 0, v[168:169]
	v_add_f32_e32 v165, 1.0, v165
	global_store_dwordx4 v[190:191], v[186:189], off nt
	v_rcp_f32_e32 v190, v165
	v_mul_f32_e32 v0, v0, v165
	v_fma_f32 v165, v111, v167, v143
	v_mul_f32_e32 v165, 0xbfb8aa3b, v165
	v_lshl_add_u64 v[186:187], s[18:19], 0, v[170:171]
	v_exp_f32_e32 v165, v165
	v_cvt_pk_bf16_f32 v182, v182, v183
	v_lshl_add_u64 v[186:187], v[186:187], 0, v[168:169]
	v_cvt_pk_bf16_f32 v183, v184, v185
	v_cvt_pk_bf16_f32 v184, v192, v193
	v_cvt_pk_bf16_f32 v185, v194, v195
	global_store_dwordx4 v[186:187], v[182:185], off nt
	v_add_f32_e32 v165, 1.0, v165
	v_rcp_f32_e32 v165, v165
	v_fma_f32 v182, v103, v167, v139
	v_mul_f32_e32 v182, 0xbfb8aa3b, v182
	v_exp_f32_e32 v182, v182
	v_fma_f32 v183, v104, v167, v140
	v_mul_f32_e32 v183, 0xbfb8aa3b, v183
	v_exp_f32_e32 v183, v183
	v_add_f32_e32 v182, 1.0, v182
	v_rcp_f32_e32 v191, v182
	v_mul_f32_e32 v165, v165, v182
	v_fma_f32 v182, v112, v167, v144
	v_mul_f32_e32 v182, 0xbfb8aa3b, v182
	v_exp_f32_e32 v182, v182
	v_add_f32_e32 v183, 1.0, v183
	v_rcp_f32_e32 v192, v183
	v_fma_f32 v184, v105, v167, v141
	v_add_f32_e32 v182, 1.0, v182
	v_rcp_f32_e32 v182, v182
	v_mul_f32_e32 v184, 0xbfb8aa3b, v184
	v_exp_f32_e32 v184, v184
	v_fma_f32 v185, v98, v167, v134
	v_mul_f32_e32 v183, v182, v183
	v_fma_f32 v182, v113, v167, v145
	v_mul_f32_e32 v182, 0xbfb8aa3b, v182
	v_exp_f32_e32 v182, v182
	v_add_f32_e32 v184, 1.0, v184
	v_rcp_f32_e32 v193, v184
	v_mul_f32_e32 v185, 0xbfb8aa3b, v185
	v_add_f32_e32 v182, 1.0, v182
	v_rcp_f32_e32 v182, v182
; __device__ __forceinline__ unsigned cvt_pk_bf16(float lo, float hi) { unsigned r; asm volatile("v_cvt_pk_bf16_f32 %0, %1, %2" : "=v"(r) : "v"(lo), "v"(hi)); return r; }
;     __device__ __forceinline__ void operator()(const AccT& acc, const Unit& u, int wr, int wc, int fr, int fq) const {
;     ...
; #pragma unroll
;             for (int ai = 0; ai < 2; ++ai)
; #pragma unroll
;                 for (int m = 0; m < 4; ++m) { const int row = row0 + ai * 128 + m * 16;
;                     const float rstd = rs[ai * 4 + m];
;                     f32x4 rt[2], sb[2];
; #pragma unroll
;                     for (int n = 0; n < 2; ++n)
; #pragma unroll
;                         for (int j = 0; j < 4; ++j) { const float ea = __builtin_amdgcn_exp2f(-LOG2E * (acc[ai][0][m][n][j] * rstd + ba[n][j])), eb = __builtin_amdgcn_exp2f(-LOG2E * (acc[ai][1][m][n][j] * rstd + bb[n][j]));
;                             sb[n][j] = __builtin_amdgcn_rcpf(1.0f + eb); rt[n][j] = (1.0f + eb) * __builtin_amdgcn_rcpf(1.0f + ea); }
;                     u32x4 w; w.x = cvt_pk_bf16(rt[0][0], rt[0][1]); w.y = cvt_pk_bf16(rt[0][2], rt[0][3]); w.z = cvt_pk_bf16(rt[1][0], rt[1][1]); w.w = cvt_pk_bf16(rt[1][2], rt[1][3]);
;                     *(u32x4*)(Z + 5 * SEC + (size_t)row * D + ch0) = w;
;                     u32x4 v; v.x = cvt_pk_bf16(sb[0][0], sb[0][1]); v.y = cvt_pk_bf16(sb[0][2], sb[0][3]); v.z = cvt_pk_bf16(sb[1][0], sb[1][1]); v.w = cvt_pk_bf16(sb[1][2], sb[1][3]);
;                     *(u32x4*)(Z + 6 * SEC + (size_t)row * D + ch0) = v; }
	v_exp_f32_e32 v185, v185
	v_fma_f32 v186, v99, v167, v135
	v_mul_f32_e32 v186, 0xbfb8aa3b, v186
	v_mul_f32_e32 v184, v182, v184
	v_fma_f32 v182, v106, v167, v130
	v_mul_f32_e32 v182, 0xbfb8aa3b, v182
	v_exp_f32_e32 v182, v182
	v_add_f32_e32 v185, 1.0, v185
	v_rcp_f32_e32 v194, v185
	v_exp_f32_e32 v186, v186
	v_add_f32_e32 v182, 1.0, v182
	v_rcp_f32_e32 v182, v182
	v_add_f32_e32 v186, 1.0, v186
	v_rcp_f32_e32 v195, v186
	v_mul_f32_e32 v185, v182, v185
	v_fma_f32 v182, v107, v167, v131
	v_mul_f32_e32 v182, 0xbfb8aa3b, v182
	v_exp_f32_e32 v182, v182
	s_nop 0
	v_add_f32_e32 v182, 1.0, v182
	v_rcp_f32_e32 v182, v182
	s_nop 0
	v_mul_f32_e32 v187, v182, v186
	v_fma_f32 v182, v108, v167, v132
	v_mul_f32_e32 v182, 0xbfb8aa3b, v182
	v_exp_f32_e32 v182, v182
	v_fma_f32 v186, v100, v167, v136
	v_mul_f32_e32 v186, 0xbfb8aa3b, v186
	v_exp_f32_e32 v186, v186
	v_add_f32_e32 v182, 1.0, v182
	v_rcp_f32_e32 v182, v182
	v_add_f32_e32 v186, 1.0, v186
	v_rcp_f32_e32 v196, v186
	v_mul_f32_e32 v188, v182, v186
	v_fma_f32 v182, v109, v167, v133
	v_mul_f32_e32 v182, 0xbfb8aa3b, v182
	v_exp_f32_e32 v182, v182
	v_fma_f32 v186, v101, v167, v137
	v_mul_f32_e32 v186, 0xbfb8aa3b, v186
	v_exp_f32_e32 v186, v186
	v_add_f32_e32 v182, 1.0, v182
	v_rcp_f32_e32 v182, v182
	v_add_f32_e32 v186, 1.0, v186
	v_rcp_f32_e32 v197, v186
	v_mul_f32_e32 v189, v182, v186
	v_cvt_pk_bf16_f32 v182, v0, v165
	v_fma_f32 v0, v94, v162, v142
	v_mul_f32_e32 v0, 0xbfb8aa3b, v0
	v_exp_f32_e32 v0, v0
	v_fma_f32 v165, v86, v162, v138
	v_mul_f32_e32 v165, 0xbfb8aa3b, v165
	v_or_b32_e32 v186, 16, v164
	v_and_b32_e32 v186, 0xfffffff0, v186
	v_exp_f32_e32 v165, v165
	v_add_f32_e32 v0, 1.0, v0
	v_cvt_pk_bf16_f32 v183, v183, v184
	v_cvt_pk_bf16_f32 v184, v185, v187
	v_ashrrev_i32_e32 v187, 31, v186
	v_rcp_f32_e32 v0, v0
	v_lshlrev_b64 v[186:187], 12, v[186:187]
	v_cvt_pk_bf16_f32 v185, v188, v189
	v_lshl_add_u64 v[188:189], s[14:15], 0, v[186:187]
	v_lshl_add_u64 v[188:189], v[188:189], 0, v[168:169]
	v_add_f32_e32 v165, 1.0, v165
	global_store_dwordx4 v[188:189], v[182:185], off nt
	v_mul_f32_e32 v0, v0, v165
	v_lshl_add_u64 v[186:187], s[18:19], 0, v[186:187]
	v_cvt_pk_bf16_f32 v182, v190, v191
	v_rcp_f32_e32 v190, v165
	v_fma_f32 v165, v95, v162, v143
	v_mul_f32_e32 v165, 0xbfb8aa3b, v165
	v_exp_f32_e32 v165, v165
	v_lshl_add_u64 v[186:187], v[186:187], 0, v[168:169]
	v_cvt_pk_bf16_f32 v183, v192, v193
	v_cvt_pk_bf16_f32 v184, v194, v195
	v_cvt_pk_bf16_f32 v185, v196, v197
	global_store_dwordx4 v[186:187], v[182:185], off nt
	v_add_f32_e32 v165, 1.0, v165
	v_rcp_f32_e32 v165, v165
	v_fma_f32 v182, v87, v162, v139
	v_mul_f32_e32 v182, 0xbfb8aa3b, v182
	v_exp_f32_e32 v182, v182
	v_fma_f32 v183, v88, v162, v140
	v_mul_f32_e32 v183, 0xbfb8aa3b, v183
	v_exp_f32_e32 v183, v183
	v_add_f32_e32 v182, 1.0, v182
	v_rcp_f32_e32 v191, v182
	v_mul_f32_e32 v165, v165, v182
	v_fma_f32 v182, v96, v162, v144
	v_mul_f32_e32 v182, 0xbfb8aa3b, v182
	v_exp_f32_e32 v182, v182
	v_add_f32_e32 v183, 1.0, v183
	v_rcp_f32_e32 v192, v183
	v_fma_f32 v184, v89, v162, v141
	v_add_f32_e32 v182, 1.0, v182
	v_rcp_f32_e32 v182, v182
	v_mul_f32_e32 v184, 0xbfb8aa3b, v184
	v_exp_f32_e32 v184, v184
	v_fma_f32 v185, v82, v162, v134
	v_mul_f32_e32 v183, v182, v183
	v_fma_f32 v182, v97, v162, v145
	v_mul_f32_e32 v182, 0xbfb8aa3b, v182
	v_exp_f32_e32 v182, v182
	v_add_f32_e32 v184, 1.0, v184
	v_rcp_f32_e32 v193, v184
	v_mul_f32_e32 v185, 0xbfb8aa3b, v185
	v_add_f32_e32 v182, 1.0, v182
	v_rcp_f32_e32 v182, v182
	v_exp_f32_e32 v185, v185
	v_fma_f32 v186, v83, v162, v135
	v_mul_f32_e32 v186, 0xbfb8aa3b, v186
	v_mul_f32_e32 v184, v182, v184
	v_fma_f32 v182, v90, v162, v130
	v_mul_f32_e32 v182, 0xbfb8aa3b, v182
	v_exp_f32_e32 v182, v182
	v_add_f32_e32 v185, 1.0, v185
	v_rcp_f32_e32 v194, v185
	v_exp_f32_e32 v186, v186
	v_add_f32_e32 v182, 1.0, v182
	v_rcp_f32_e32 v182, v182
	v_add_f32_e32 v186, 1.0, v186
	v_rcp_f32_e32 v195, v186
	v_mul_f32_e32 v185, v182, v185
	v_fma_f32 v182, v91, v162, v131
	v_mul_f32_e32 v182, 0xbfb8aa3b, v182
	v_exp_f32_e32 v182, v182
	s_nop 0
	v_add_f32_e32 v182, 1.0, v182
	v_rcp_f32_e32 v182, v182
	s_nop 0
	v_mul_f32_e32 v187, v182, v186
	v_fma_f32 v182, v92, v162, v132
	v_mul_f32_e32 v182, 0xbfb8aa3b, v182
	v_exp_f32_e32 v182, v182
	v_fma_f32 v186, v84, v162, v136
	v_mul_f32_e32 v186, 0xbfb8aa3b, v186
	v_exp_f32_e32 v186, v186
	v_add_f32_e32 v182, 1.0, v182
	v_rcp_f32_e32 v182, v182
	v_add_f32_e32 v186, 1.0, v186
	v_rcp_f32_e32 v196, v186
	v_mul_f32_e32 v188, v182, v186
	v_fma_f32 v182, v93, v162, v133
	v_mul_f32_e32 v182, 0xbfb8aa3b, v182
	v_exp_f32_e32 v182, v182
	v_fma_f32 v186, v85, v162, v137
	v_mul_f32_e32 v186, 0xbfb8aa3b, v186
	v_exp_f32_e32 v186, v186
	v_add_f32_e32 v182, 1.0, v182
	v_rcp_f32_e32 v182, v182
	v_add_f32_e32 v186, 1.0, v186
	v_rcp_f32_e32 v197, v186
	v_mul_f32_e32 v189, v182, v186
	v_cvt_pk_bf16_f32 v182, v0, v165
	v_fma_f32 v0, v78, v163, v142
	v_mul_f32_e32 v0, 0xbfb8aa3b, v0
	v_exp_f32_e32 v0, v0
	v_fma_f32 v165, v70, v163, v138
	v_mul_f32_e32 v165, 0xbfb8aa3b, v165
	v_or_b32_e32 v186, 32, v164
	v_and_b32_e32 v186, 0xfffffff0, v186
	v_exp_f32_e32 v165, v165
	v_add_f32_e32 v0, 1.0, v0
	v_cvt_pk_bf16_f32 v183, v183, v184
	v_cvt_pk_bf16_f32 v184, v185, v187
	v_ashrrev_i32_e32 v187, 31, v186
	v_rcp_f32_e32 v0, v0
	v_lshlrev_b64 v[186:187], 12, v[186:187]
	v_cvt_pk_bf16_f32 v185, v188, v189
	v_lshl_add_u64 v[188:189], s[14:15], 0, v[186:187]
	v_lshl_add_u64 v[188:189], v[188:189], 0, v[168:169]
	v_add_f32_e32 v165, 1.0, v165
	global_store_dwordx4 v[188:189], v[182:185], off nt
	v_mul_f32_e32 v0, v0, v165
	v_lshl_add_u64 v[186:187], s[18:19], 0, v[186:187]
	v_cvt_pk_bf16_f32 v182, v190, v191
; __device__ __forceinline__ unsigned cvt_pk_bf16(float lo, float hi) { unsigned r; asm volatile("v_cvt_pk_bf16_f32 %0, %1, %2" : "=v"(r) : "v"(lo), "v"(hi)); return r; }
;     __device__ __forceinline__ void operator()(const AccT& acc, const Unit& u, int wr, int wc, int fr, int fq) const {
;     ...
; #pragma unroll
;             for (int ai = 0; ai < 2; ++ai)
; #pragma unroll
;                 for (int m = 0; m < 4; ++m) { const int row = row0 + ai * 128 + m * 16;
;                     const float rstd = rs[ai * 4 + m];
;                     f32x4 rt[2], sb[2];
; #pragma unroll
;                     for (int n = 0; n < 2; ++n)
; #pragma unroll
;                         for (int j = 0; j < 4; ++j) { const float ea = __builtin_amdgcn_exp2f(-LOG2E * (acc[ai][0][m][n][j] * rstd + ba[n][j])), eb = __builtin_amdgcn_exp2f(-LOG2E * (acc[ai][1][m][n][j] * rstd + bb[n][j]));
;                             sb[n][j] = __builtin_amdgcn_rcpf(1.0f + eb); rt[n][j] = (1.0f + eb) * __builtin_amdgcn_rcpf(1.0f + ea); }
;                     u32x4 w; w.x = cvt_pk_bf16(rt[0][0], rt[0][1]); w.y = cvt_pk_bf16(rt[0][2], rt[0][3]); w.z = cvt_pk_bf16(rt[1][0], rt[1][1]); w.w = cvt_pk_bf16(rt[1][2], rt[1][3]);
;                     *(u32x4*)(Z + 5 * SEC + (size_t)row * D + ch0) = w;
;                     u32x4 v; v.x = cvt_pk_bf16(sb[0][0], sb[0][1]); v.y = cvt_pk_bf16(sb[0][2], sb[0][3]); v.z = cvt_pk_bf16(sb[1][0], sb[1][1]); v.w = cvt_pk_bf16(sb[1][2], sb[1][3]);
;                     *(u32x4*)(Z + 6 * SEC + (size_t)row * D + ch0) = v; }
	v_rcp_f32_e32 v190, v165
	v_fma_f32 v165, v79, v163, v143
	v_mul_f32_e32 v165, 0xbfb8aa3b, v165
	v_exp_f32_e32 v165, v165
	v_lshl_add_u64 v[186:187], v[186:187], 0, v[168:169]
	v_cvt_pk_bf16_f32 v183, v192, v193
	v_cvt_pk_bf16_f32 v184, v194, v195
	v_cvt_pk_bf16_f32 v185, v196, v197
	global_store_dwordx4 v[186:187], v[182:185], off nt
	v_add_f32_e32 v165, 1.0, v165
	v_rcp_f32_e32 v165, v165
	v_fma_f32 v182, v71, v163, v139
	v_mul_f32_e32 v182, 0xbfb8aa3b, v182
	v_exp_f32_e32 v182, v182
	v_fma_f32 v183, v72, v163, v140
	v_mul_f32_e32 v183, 0xbfb8aa3b, v183
	v_exp_f32_e32 v183, v183
	v_add_f32_e32 v182, 1.0, v182
	v_rcp_f32_e32 v191, v182
	v_mul_f32_e32 v165, v165, v182
	v_fma_f32 v182, v80, v163, v144
	v_mul_f32_e32 v182, 0xbfb8aa3b, v182
	v_exp_f32_e32 v182, v182
	v_add_f32_e32 v183, 1.0, v183
	v_rcp_f32_e32 v192, v183
	v_fma_f32 v184, v73, v163, v141
	v_add_f32_e32 v182, 1.0, v182
	v_rcp_f32_e32 v182, v182
	v_mul_f32_e32 v184, 0xbfb8aa3b, v184
	v_exp_f32_e32 v184, v184
	v_fma_f32 v185, v66, v163, v134
	v_mul_f32_e32 v183, v182, v183
	v_fma_f32 v182, v81, v163, v145
	v_mul_f32_e32 v182, 0xbfb8aa3b, v182
	v_exp_f32_e32 v182, v182
	v_add_f32_e32 v184, 1.0, v184
	v_rcp_f32_e32 v193, v184
	v_mul_f32_e32 v185, 0xbfb8aa3b, v185
	v_add_f32_e32 v182, 1.0, v182
	v_rcp_f32_e32 v182, v182
	v_exp_f32_e32 v185, v185
	v_fma_f32 v186, v67, v163, v135
	v_mul_f32_e32 v186, 0xbfb8aa3b, v186
	v_mul_f32_e32 v184, v182, v184
	v_fma_f32 v182, v74, v163, v130
	v_mul_f32_e32 v182, 0xbfb8aa3b, v182
	v_exp_f32_e32 v182, v182
	v_add_f32_e32 v185, 1.0, v185
	v_rcp_f32_e32 v194, v185
	v_exp_f32_e32 v186, v186
	v_add_f32_e32 v182, 1.0, v182
	v_rcp_f32_e32 v182, v182
	v_add_f32_e32 v186, 1.0, v186
	v_rcp_f32_e32 v195, v186
	v_mul_f32_e32 v185, v182, v185
	v_fma_f32 v182, v75, v163, v131
	v_mul_f32_e32 v182, 0xbfb8aa3b, v182
	v_exp_f32_e32 v182, v182
	s_nop 0
	v_add_f32_e32 v182, 1.0, v182
	v_rcp_f32_e32 v182, v182
	s_nop 0
	v_mul_f32_e32 v187, v182, v186
	v_fma_f32 v182, v76, v163, v132
	v_mul_f32_e32 v182, 0xbfb8aa3b, v182
	v_exp_f32_e32 v182, v182
	v_fma_f32 v186, v68, v163, v136
	v_mul_f32_e32 v186, 0xbfb8aa3b, v186
	v_exp_f32_e32 v186, v186
	v_add_f32_e32 v182, 1.0, v182
	v_rcp_f32_e32 v182, v182
	v_add_f32_e32 v186, 1.0, v186
	v_rcp_f32_e32 v196, v186
	v_mul_f32_e32 v188, v182, v186
	v_fma_f32 v182, v77, v163, v133
	v_mul_f32_e32 v182, 0xbfb8aa3b, v182
	v_exp_f32_e32 v182, v182
	v_fma_f32 v186, v69, v163, v137
	v_mul_f32_e32 v186, 0xbfb8aa3b, v186
	v_exp_f32_e32 v186, v186
	v_add_f32_e32 v182, 1.0, v182
	v_rcp_f32_e32 v182, v182
	v_add_f32_e32 v186, 1.0, v186
	v_rcp_f32_e32 v197, v186
	v_mul_f32_e32 v189, v182, v186
	v_cvt_pk_bf16_f32 v182, v0, v165
	v_fma_f32 v0, v62, v160, v142
	v_mul_f32_e32 v0, 0xbfb8aa3b, v0
	v_exp_f32_e32 v0, v0
	v_fma_f32 v165, v54, v160, v138
	v_mul_f32_e32 v165, 0xbfb8aa3b, v165
	v_or_b32_e32 v186, 48, v164
	v_and_b32_e32 v186, 0xfffffff0, v186
	v_exp_f32_e32 v165, v165
	v_add_f32_e32 v0, 1.0, v0
	v_cvt_pk_bf16_f32 v183, v183, v184
	v_cvt_pk_bf16_f32 v184, v185, v187
	v_ashrrev_i32_e32 v187, 31, v186
	v_rcp_f32_e32 v0, v0
	v_lshlrev_b64 v[186:187], 12, v[186:187]
	v_cvt_pk_bf16_f32 v185, v188, v189
	v_lshl_add_u64 v[188:189], s[14:15], 0, v[186:187]
	v_lshl_add_u64 v[188:189], v[188:189], 0, v[168:169]
	v_add_f32_e32 v165, 1.0, v165
	global_store_dwordx4 v[188:189], v[182:185], off nt
	v_mul_f32_e32 v0, v0, v165
	v_lshl_add_u64 v[186:187], s[18:19], 0, v[186:187]
	v_cvt_pk_bf16_f32 v182, v190, v191
	v_rcp_f32_e32 v190, v165
	v_fma_f32 v165, v63, v160, v143
	v_mul_f32_e32 v165, 0xbfb8aa3b, v165
	v_exp_f32_e32 v165, v165
	v_lshl_add_u64 v[186:187], v[186:187], 0, v[168:169]
	v_cvt_pk_bf16_f32 v183, v192, v193
	v_cvt_pk_bf16_f32 v184, v194, v195
	v_cvt_pk_bf16_f32 v185, v196, v197
	global_store_dwordx4 v[186:187], v[182:185], off nt
	v_add_f32_e32 v165, 1.0, v165
	v_rcp_f32_e32 v165, v165
	v_fma_f32 v182, v55, v160, v139
	v_mul_f32_e32 v182, 0xbfb8aa3b, v182
	v_exp_f32_e32 v182, v182
	v_fma_f32 v183, v56, v160, v140
	v_mul_f32_e32 v183, 0xbfb8aa3b, v183
	v_exp_f32_e32 v183, v183
	v_add_f32_e32 v182, 1.0, v182
	v_rcp_f32_e32 v191, v182
	v_mul_f32_e32 v165, v165, v182
	v_fma_f32 v182, v64, v160, v144
	v_mul_f32_e32 v182, 0xbfb8aa3b, v182
	v_exp_f32_e32 v182, v182
	v_add_f32_e32 v183, 1.0, v183
	v_rcp_f32_e32 v192, v183
	v_fma_f32 v184, v57, v160, v141
	v_add_f32_e32 v182, 1.0, v182
	v_rcp_f32_e32 v182, v182
	v_mul_f32_e32 v184, 0xbfb8aa3b, v184
	v_exp_f32_e32 v184, v184
	v_fma_f32 v185, v50, v160, v134
	v_mul_f32_e32 v183, v182, v183
	v_fma_f32 v182, v65, v160, v145
	v_mul_f32_e32 v182, 0xbfb8aa3b, v182
	v_exp_f32_e32 v182, v182
	v_add_f32_e32 v184, 1.0, v184
	v_rcp_f32_e32 v193, v184
	v_mul_f32_e32 v185, 0xbfb8aa3b, v185
	v_add_f32_e32 v182, 1.0, v182
	v_rcp_f32_e32 v182, v182
	v_exp_f32_e32 v185, v185
	v_fma_f32 v186, v51, v160, v135
	v_mul_f32_e32 v186, 0xbfb8aa3b, v186
	v_mul_f32_e32 v184, v182, v184
	v_fma_f32 v182, v58, v160, v130
	v_mul_f32_e32 v182, 0xbfb8aa3b, v182
	v_exp_f32_e32 v182, v182
	v_add_f32_e32 v185, 1.0, v185
	v_rcp_f32_e32 v194, v185
	v_exp_f32_e32 v186, v186
	v_add_f32_e32 v182, 1.0, v182
	v_rcp_f32_e32 v182, v182
	v_fma_f32 v187, v52, v160, v136
	v_add_f32_e32 v186, 1.0, v186
	v_rcp_f32_e32 v195, v186
	v_mul_f32_e32 v185, v182, v185
	v_fma_f32 v182, v59, v160, v131
	v_mul_f32_e32 v182, 0xbfb8aa3b, v182
	v_exp_f32_e32 v182, v182
	v_mul_f32_e32 v187, 0xbfb8aa3b, v187
	v_exp_f32_e32 v187, v187
	v_fma_f32 v188, v53, v160, v137
	v_add_f32_e32 v182, 1.0, v182
	v_rcp_f32_e32 v182, v182
	v_add_f32_e32 v187, 1.0, v187
	v_rcp_f32_e32 v196, v187
	v_mul_f32_e32 v188, 0xbfb8aa3b, v188
	v_mul_f32_e32 v186, v182, v186
; __device__ __forceinline__ unsigned cvt_pk_bf16(float lo, float hi) { unsigned r; asm volatile("v_cvt_pk_bf16_f32 %0, %1, %2" : "=v"(r) : "v"(lo), "v"(hi)); return r; }
;     __device__ __forceinline__ void operator()(const AccT& acc, const Unit& u, int wr, int wc, int fr, int fq) const {
;     ...
; #pragma unroll
;             for (int ai = 0; ai < 2; ++ai)
; #pragma unroll
;                 for (int m = 0; m < 4; ++m) { const int row = row0 + ai * 128 + m * 16;
;                     const float rstd = rs[ai * 4 + m];
;                     f32x4 rt[2], sb[2];
; #pragma unroll
;                     for (int n = 0; n < 2; ++n)
; #pragma unroll
;                         for (int j = 0; j < 4; ++j) { const float ea = __builtin_amdgcn_exp2f(-LOG2E * (acc[ai][0][m][n][j] * rstd + ba[n][j])), eb = __builtin_amdgcn_exp2f(-LOG2E * (acc[ai][1][m][n][j] * rstd + bb[n][j]));
;                             sb[n][j] = __builtin_amdgcn_rcpf(1.0f + eb); rt[n][j] = (1.0f + eb) * __builtin_amdgcn_rcpf(1.0f + ea); }
;                     u32x4 w; w.x = cvt_pk_bf16(rt[0][0], rt[0][1]); w.y = cvt_pk_bf16(rt[0][2], rt[0][3]); w.z = cvt_pk_bf16(rt[1][0], rt[1][1]); w.w = cvt_pk_bf16(rt[1][2], rt[1][3]);
;                     *(u32x4*)(Z + 5 * SEC + (size_t)row * D + ch0) = w;
;                     u32x4 v; v.x = cvt_pk_bf16(sb[0][0], sb[0][1]); v.y = cvt_pk_bf16(sb[0][2], sb[0][3]); v.z = cvt_pk_bf16(sb[1][0], sb[1][1]); v.w = cvt_pk_bf16(sb[1][2], sb[1][3]);
;                     *(u32x4*)(Z + 6 * SEC + (size_t)row * D + ch0) = v; }
	v_fma_f32 v182, v60, v160, v132
	v_mul_f32_e32 v182, 0xbfb8aa3b, v182
	v_exp_f32_e32 v182, v182
	v_exp_f32_e32 v188, v188
	v_add_f32_e32 v182, 1.0, v182
	v_rcp_f32_e32 v182, v182
	v_add_f32_e32 v188, 1.0, v188
	v_rcp_f32_e32 v197, v188
	v_mul_f32_e32 v187, v182, v187
	v_fma_f32 v182, v61, v160, v133
	v_mul_f32_e32 v182, 0xbfb8aa3b, v182
	v_exp_f32_e32 v182, v182
	s_nop 0
	v_add_f32_e32 v182, 1.0, v182
	v_rcp_f32_e32 v182, v182
	s_nop 0
	v_mul_f32_e32 v188, v182, v188
	v_cvt_pk_bf16_f32 v182, v0, v165
	v_fma_f32 v0, v46, v161, v142
	v_mul_f32_e32 v0, 0xbfb8aa3b, v0
	v_exp_f32_e32 v0, v0
	v_fma_f32 v165, v38, v161, v138
	v_mul_f32_e32 v165, 0xbfb8aa3b, v165
	v_exp_f32_e32 v165, v165
	v_add_f32_e32 v0, 1.0, v0
	v_rcp_f32_e32 v0, v0
	v_cvt_pk_bf16_f32 v183, v183, v184
	v_cvt_pk_bf16_f32 v184, v185, v186
	v_cvt_pk_bf16_f32 v185, v187, v188
	v_lshl_add_u64 v[186:187], v[170:171], 0, s[16:17]
	v_lshl_add_u64 v[188:189], s[14:15], 0, v[186:187]
	v_lshl_add_u64 v[188:189], v[188:189], 0, v[168:169]
	v_add_f32_e32 v165, 1.0, v165
	global_store_dwordx4 v[188:189], v[182:185], off nt
	v_mul_f32_e32 v0, v0, v165
	v_lshl_add_u64 v[186:187], s[18:19], 0, v[186:187]
	v_cvt_pk_bf16_f32 v182, v190, v191
	v_rcp_f32_e32 v190, v165
	v_fma_f32 v165, v47, v161, v143
	v_mul_f32_e32 v165, 0xbfb8aa3b, v165
	v_exp_f32_e32 v165, v165
	v_lshl_add_u64 v[186:187], v[186:187], 0, v[168:169]
	v_cvt_pk_bf16_f32 v183, v192, v193
	v_cvt_pk_bf16_f32 v184, v194, v195
	v_cvt_pk_bf16_f32 v185, v196, v197
	global_store_dwordx4 v[186:187], v[182:185], off nt
	v_add_f32_e32 v165, 1.0, v165
	v_rcp_f32_e32 v165, v165
	v_fma_f32 v182, v39, v161, v139
	v_mul_f32_e32 v182, 0xbfb8aa3b, v182
	v_exp_f32_e32 v182, v182
	v_fma_f32 v183, v40, v161, v140
	v_mul_f32_e32 v183, 0xbfb8aa3b, v183
	v_exp_f32_e32 v183, v183
	v_add_f32_e32 v182, 1.0, v182
	v_rcp_f32_e32 v191, v182
	v_mul_f32_e32 v165, v165, v182
	v_fma_f32 v182, v48, v161, v144
	v_mul_f32_e32 v182, 0xbfb8aa3b, v182
	v_exp_f32_e32 v182, v182
	v_add_f32_e32 v183, 1.0, v183
	v_rcp_f32_e32 v192, v183
	v_fma_f32 v184, v41, v161, v141
	v_add_f32_e32 v182, 1.0, v182
	v_rcp_f32_e32 v182, v182
	v_mul_f32_e32 v184, 0xbfb8aa3b, v184
	v_exp_f32_e32 v184, v184
	v_fma_f32 v185, v34, v161, v134
	v_mul_f32_e32 v183, v182, v183
	v_fma_f32 v182, v49, v161, v145
	v_mul_f32_e32 v182, 0xbfb8aa3b, v182
	v_exp_f32_e32 v182, v182
	v_add_f32_e32 v184, 1.0, v184
	v_rcp_f32_e32 v193, v184
	v_mul_f32_e32 v185, 0xbfb8aa3b, v185
	v_add_f32_e32 v182, 1.0, v182
	v_rcp_f32_e32 v182, v182
	v_exp_f32_e32 v185, v185
	v_fma_f32 v186, v35, v161, v135
	v_mul_f32_e32 v186, 0xbfb8aa3b, v186
	v_mul_f32_e32 v184, v182, v184
	v_fma_f32 v182, v42, v161, v130
	v_mul_f32_e32 v182, 0xbfb8aa3b, v182
	v_exp_f32_e32 v182, v182
	v_add_f32_e32 v185, 1.0, v185
	v_rcp_f32_e32 v194, v185
	v_exp_f32_e32 v186, v186
	v_add_f32_e32 v182, 1.0, v182
	v_rcp_f32_e32 v182, v182
	v_fma_f32 v187, v36, v161, v136
	v_add_f32_e32 v186, 1.0, v186
	v_rcp_f32_e32 v195, v186
	v_mul_f32_e32 v185, v182, v185
	v_fma_f32 v182, v43, v161, v131
	v_mul_f32_e32 v182, 0xbfb8aa3b, v182
	v_exp_f32_e32 v182, v182
	v_mul_f32_e32 v187, 0xbfb8aa3b, v187
	v_exp_f32_e32 v187, v187
	v_fma_f32 v188, v37, v161, v137
	v_add_f32_e32 v182, 1.0, v182
	v_rcp_f32_e32 v182, v182
	v_add_f32_e32 v187, 1.0, v187
	v_rcp_f32_e32 v196, v187
	v_mul_f32_e32 v188, 0xbfb8aa3b, v188
	v_mul_f32_e32 v186, v182, v186
	v_fma_f32 v182, v44, v161, v132
	v_mul_f32_e32 v182, 0xbfb8aa3b, v182
	v_exp_f32_e32 v182, v182
	v_exp_f32_e32 v188, v188
	v_add_f32_e32 v182, 1.0, v182
	v_rcp_f32_e32 v182, v182
	v_add_f32_e32 v188, 1.0, v188
	v_rcp_f32_e32 v197, v188
	v_mul_f32_e32 v187, v182, v187
	v_fma_f32 v182, v45, v161, v133
	v_mul_f32_e32 v182, 0xbfb8aa3b, v182
	v_exp_f32_e32 v182, v182
	s_nop 0
	v_add_f32_e32 v182, 1.0, v182
	v_rcp_f32_e32 v182, v182
	s_nop 0
	v_mul_f32_e32 v188, v182, v188
	v_cvt_pk_bf16_f32 v182, v0, v165
	v_fma_f32 v0, v30, v158, v142
	v_mul_f32_e32 v0, 0xbfb8aa3b, v0
	v_exp_f32_e32 v0, v0
	v_fma_f32 v165, v22, v158, v138
	v_mul_f32_e32 v165, 0xbfb8aa3b, v165
	v_exp_f32_e32 v165, v165
	v_add_f32_e32 v0, 1.0, v0
	v_rcp_f32_e32 v0, v0
	v_cvt_pk_bf16_f32 v183, v183, v184
	v_cvt_pk_bf16_f32 v184, v185, v186
	v_cvt_pk_bf16_f32 v185, v187, v188
	v_lshl_add_u64 v[186:187], v[170:171], 0, s[58:59]
	v_lshl_add_u64 v[188:189], s[14:15], 0, v[186:187]
	v_lshl_add_u64 v[188:189], v[188:189], 0, v[168:169]
	v_add_f32_e32 v165, 1.0, v165
	global_store_dwordx4 v[188:189], v[182:185], off nt
	v_mul_f32_e32 v0, v0, v165
	v_lshl_add_u64 v[186:187], s[18:19], 0, v[186:187]
	v_cvt_pk_bf16_f32 v182, v190, v191
	v_rcp_f32_e32 v190, v165
	v_fma_f32 v165, v31, v158, v143
	v_mul_f32_e32 v165, 0xbfb8aa3b, v165
	v_exp_f32_e32 v165, v165
	v_lshl_add_u64 v[186:187], v[186:187], 0, v[168:169]
	v_cvt_pk_bf16_f32 v183, v192, v193
	v_cvt_pk_bf16_f32 v184, v194, v195
	v_cvt_pk_bf16_f32 v185, v196, v197
	global_store_dwordx4 v[186:187], v[182:185], off nt
	v_add_f32_e32 v165, 1.0, v165
	v_rcp_f32_e32 v165, v165
	v_fma_f32 v182, v23, v158, v139
	v_mul_f32_e32 v182, 0xbfb8aa3b, v182
	v_exp_f32_e32 v182, v182
	v_fma_f32 v183, v24, v158, v140
	v_mul_f32_e32 v183, 0xbfb8aa3b, v183
	v_exp_f32_e32 v183, v183
	v_add_f32_e32 v182, 1.0, v182
	v_rcp_f32_e32 v191, v182
	v_mul_f32_e32 v165, v165, v182
	v_fma_f32 v182, v32, v158, v144
	v_mul_f32_e32 v182, 0xbfb8aa3b, v182
	v_exp_f32_e32 v182, v182
	v_add_f32_e32 v183, 1.0, v183
	v_rcp_f32_e32 v192, v183
	v_fma_f32 v184, v25, v158, v141
	v_add_f32_e32 v182, 1.0, v182
	v_rcp_f32_e32 v182, v182
	v_mul_f32_e32 v184, 0xbfb8aa3b, v184
	v_exp_f32_e32 v184, v184
	v_fma_f32 v185, v18, v158, v134
; __device__ __forceinline__ unsigned cvt_pk_bf16(float lo, float hi) { unsigned r; asm volatile("v_cvt_pk_bf16_f32 %0, %1, %2" : "=v"(r) : "v"(lo), "v"(hi)); return r; }
;     __device__ __forceinline__ void operator()(const AccT& acc, const Unit& u, int wr, int wc, int fr, int fq) const {
;     ...
; #pragma unroll
;             for (int ai = 0; ai < 2; ++ai)
; #pragma unroll
;                 for (int m = 0; m < 4; ++m) { const int row = row0 + ai * 128 + m * 16;
;                     const float rstd = rs[ai * 4 + m];
;                     f32x4 rt[2], sb[2];
; #pragma unroll
;                     for (int n = 0; n < 2; ++n)
; #pragma unroll
;                         for (int j = 0; j < 4; ++j) { const float ea = __builtin_amdgcn_exp2f(-LOG2E * (acc[ai][0][m][n][j] * rstd + ba[n][j])), eb = __builtin_amdgcn_exp2f(-LOG2E * (acc[ai][1][m][n][j] * rstd + bb[n][j]));
;                             sb[n][j] = __builtin_amdgcn_rcpf(1.0f + eb); rt[n][j] = (1.0f + eb) * __builtin_amdgcn_rcpf(1.0f + ea); }
;                     u32x4 w; w.x = cvt_pk_bf16(rt[0][0], rt[0][1]); w.y = cvt_pk_bf16(rt[0][2], rt[0][3]); w.z = cvt_pk_bf16(rt[1][0], rt[1][1]); w.w = cvt_pk_bf16(rt[1][2], rt[1][3]);
;                     *(u32x4*)(Z + 5 * SEC + (size_t)row * D + ch0) = w;
;                     u32x4 v; v.x = cvt_pk_bf16(sb[0][0], sb[0][1]); v.y = cvt_pk_bf16(sb[0][2], sb[0][3]); v.z = cvt_pk_bf16(sb[1][0], sb[1][1]); v.w = cvt_pk_bf16(sb[1][2], sb[1][3]);
;                     *(u32x4*)(Z + 6 * SEC + (size_t)row * D + ch0) = v; }
	v_mul_f32_e32 v183, v182, v183
	v_fma_f32 v182, v33, v158, v145
	v_mul_f32_e32 v182, 0xbfb8aa3b, v182
	v_exp_f32_e32 v182, v182
	v_add_f32_e32 v184, 1.0, v184
	v_rcp_f32_e32 v193, v184
	v_mul_f32_e32 v185, 0xbfb8aa3b, v185
	v_add_f32_e32 v182, 1.0, v182
	v_rcp_f32_e32 v182, v182
	v_exp_f32_e32 v185, v185
	v_fma_f32 v186, v19, v158, v135
	v_mul_f32_e32 v186, 0xbfb8aa3b, v186
	v_mul_f32_e32 v184, v182, v184
	v_fma_f32 v182, v26, v158, v130
	v_mul_f32_e32 v182, 0xbfb8aa3b, v182
	v_exp_f32_e32 v182, v182
	v_add_f32_e32 v185, 1.0, v185
	v_rcp_f32_e32 v194, v185
	v_exp_f32_e32 v186, v186
	v_add_f32_e32 v182, 1.0, v182
	v_rcp_f32_e32 v182, v182
	v_fma_f32 v187, v20, v158, v136
	v_add_f32_e32 v186, 1.0, v186
	v_rcp_f32_e32 v195, v186
	v_mul_f32_e32 v185, v182, v185
	v_fma_f32 v182, v27, v158, v131
	v_mul_f32_e32 v182, 0xbfb8aa3b, v182
	v_exp_f32_e32 v182, v182
	v_mul_f32_e32 v187, 0xbfb8aa3b, v187
	v_exp_f32_e32 v187, v187
	v_fma_f32 v188, v21, v158, v137
	v_add_f32_e32 v182, 1.0, v182
	v_rcp_f32_e32 v182, v182
	v_add_f32_e32 v187, 1.0, v187
	v_rcp_f32_e32 v196, v187
	v_mul_f32_e32 v188, 0xbfb8aa3b, v188
	v_mul_f32_e32 v186, v182, v186
	v_fma_f32 v182, v28, v158, v132
	v_mul_f32_e32 v182, 0xbfb8aa3b, v182
	v_exp_f32_e32 v182, v182
	v_exp_f32_e32 v188, v188
	v_fma_f32 v138, v6, v159, v138
	v_mul_f32_e32 v138, 0xbfb8aa3b, v138
	v_add_f32_e32 v182, 1.0, v182
	v_rcp_f32_e32 v182, v182
	v_add_f32_e32 v188, 1.0, v188
	v_rcp_f32_e32 v197, v188
	v_exp_f32_e32 v138, v138
	v_mul_f32_e32 v187, v182, v187
	v_fma_f32 v182, v29, v158, v133
	v_mul_f32_e32 v182, 0xbfb8aa3b, v182
	v_exp_f32_e32 v182, v182
	v_add_f32_e32 v138, 1.0, v138
	v_fma_f32 v139, v7, v159, v139
	v_mul_f32_e32 v139, 0xbfb8aa3b, v139
	v_add_f32_e32 v182, 1.0, v182
	v_rcp_f32_e32 v182, v182
	v_exp_f32_e32 v139, v139
	v_fma_f32 v140, v8, v159, v140
	v_mul_f32_e32 v140, 0xbfb8aa3b, v140
	v_mul_f32_e32 v188, v182, v188
	v_cvt_pk_bf16_f32 v182, v0, v165
	v_fma_f32 v0, v14, v159, v142
	v_mul_f32_e32 v0, 0xbfb8aa3b, v0
	v_exp_f32_e32 v0, v0
	v_rcp_f32_e32 v142, v138
	v_add_f32_e32 v139, 1.0, v139
	v_exp_f32_e32 v140, v140
	v_add_f32_e32 v0, 1.0, v0
	v_rcp_f32_e32 v0, v0
	v_fmac_f32_e32 v145, v17, v159
	v_add_f32_e32 v140, 1.0, v140
	v_fma_f32 v130, v10, v159, v130
	v_mul_f32_e32 v0, v0, v138
	v_fma_f32 v138, v15, v159, v143
	v_mul_f32_e32 v138, 0xbfb8aa3b, v138
	v_exp_f32_e32 v138, v138
	v_rcp_f32_e32 v143, v139
	v_mul_f32_e32 v130, 0xbfb8aa3b, v130
	v_exp_f32_e32 v130, v130
	v_add_f32_e32 v138, 1.0, v138
	v_rcp_f32_e32 v138, v138
	v_fmac_f32_e32 v141, v9, v159
	v_fma_f32 v134, v2, v159, v134
	v_mul_f32_e32 v141, 0xbfb8aa3b, v141
	v_mul_f32_e32 v138, v138, v139
	v_fma_f32 v139, v16, v159, v144
	v_mul_f32_e32 v139, 0xbfb8aa3b, v139
	v_exp_f32_e32 v139, v139
	v_rcp_f32_e32 v144, v140
	v_mul_f32_e32 v134, 0xbfb8aa3b, v134
	v_exp_f32_e32 v141, v141
	v_add_f32_e32 v139, 1.0, v139
	v_rcp_f32_e32 v139, v139
	v_exp_f32_e32 v134, v134
	v_add_f32_e32 v130, 1.0, v130
	v_rcp_f32_e32 v130, v130
	v_mul_f32_e32 v139, v139, v140
	v_mul_f32_e32 v140, 0xbfb8aa3b, v145
	v_exp_f32_e32 v140, v140
	v_add_f32_e32 v141, 1.0, v141
	v_add_f32_e32 v134, 1.0, v134
	v_rcp_f32_e32 v145, v141
	v_add_f32_e32 v140, 1.0, v140
	v_rcp_f32_e32 v140, v140
	v_fmac_f32_e32 v133, v13, v159
	v_cvt_pk_bf16_f32 v183, v183, v184
	v_cvt_pk_bf16_f32 v184, v185, v186
	v_mul_f32_e32 v140, v140, v141
	v_rcp_f32_e32 v141, v134
	v_mul_f32_e32 v134, v130, v134
	v_fma_f32 v130, v11, v159, v131
	v_mul_f32_e32 v130, 0xbfb8aa3b, v130
	v_exp_f32_e32 v130, v130
	v_fma_f32 v131, v3, v159, v135
	v_mul_f32_e32 v131, 0xbfb8aa3b, v131
	v_exp_f32_e32 v131, v131
	v_add_f32_e32 v130, 1.0, v130
	v_rcp_f32_e32 v130, v130
	v_cvt_pk_bf16_f32 v185, v187, v188
	v_add_f32_e32 v131, 1.0, v131
	v_rcp_f32_e32 v165, v131
	v_mul_f32_e32 v135, v130, v131
	v_fma_f32 v130, v12, v159, v132
	v_mul_f32_e32 v130, 0xbfb8aa3b, v130
	v_exp_f32_e32 v130, v130
	v_fma_f32 v131, v4, v159, v136
	v_mul_f32_e32 v131, 0xbfb8aa3b, v131
	v_exp_f32_e32 v131, v131
	v_add_f32_e32 v130, 1.0, v130
	v_rcp_f32_e32 v130, v130
	v_lshl_add_u64 v[186:187], v[170:171], 0, s[86:87]
	v_add_f32_e32 v131, 1.0, v131
	v_lshl_add_u64 v[188:189], s[14:15], 0, v[186:187]
	v_mul_f32_e32 v136, v130, v131
	v_mul_f32_e32 v130, 0xbfb8aa3b, v133
	v_exp_f32_e32 v130, v130
	v_lshl_add_u64 v[188:189], v[188:189], 0, v[168:169]
	v_lshl_add_u64 v[186:187], s[18:19], 0, v[186:187]
	global_store_dwordx4 v[188:189], v[182:185], off nt
	v_lshl_add_u64 v[186:187], v[186:187], 0, v[168:169]
	v_fmac_f32_e32 v137, v5, v159
	v_cvt_pk_bf16_f32 v182, v190, v191
	v_cvt_pk_bf16_f32 v183, v192, v193
	v_cvt_pk_bf16_f32 v184, v194, v195
	v_cvt_pk_bf16_f32 v185, v196, v197
	global_store_dwordx4 v[186:187], v[182:185], off nt
	v_add_f32_e32 v130, 1.0, v130
	v_rcp_f32_e32 v130, v130
	v_rcp_f32_e32 v182, v131
	v_mul_f32_e32 v131, 0xbfb8aa3b, v137
	v_exp_f32_e32 v131, v131
	s_nop 0
	v_add_f32_e32 v131, 1.0, v131
	v_rcp_f32_e32 v183, v131
	v_mul_f32_e32 v133, v130, v131
	v_cvt_pk_bf16_f32 v130, v0, v138
	v_cvt_pk_bf16_f32 v131, v139, v140
	v_cvt_pk_bf16_f32 v132, v134, v135
	v_lshl_add_u64 v[134:135], v[170:171], 0, s[94:95]
	v_cvt_pk_bf16_f32 v133, v136, v133
	v_lshl_add_u64 v[136:137], s[14:15], 0, v[134:135]
	v_lshl_add_u64 v[134:135], s[18:19], 0, v[134:135]
	v_lshl_add_u64 v[136:137], v[136:137], 0, v[168:169]
	v_lshl_add_u64 v[134:135], v[134:135], 0, v[168:169]
	global_store_dwordx4 v[136:137], v[130:133], off nt
	s_nop 1
	v_cvt_pk_bf16_f32 v130, v142, v143
	v_cvt_pk_bf16_f32 v131, v144, v145
	v_cvt_pk_bf16_f32 v132, v141, v165
	v_cvt_pk_bf16_f32 v133, v182, v183
	global_store_dwordx4 v[134:135], v[130:133], off nt

;     __device__ __forceinline__ void mid(AccT& acc, const Unit& u, int wr, int wc, int fr, int fq) const {
;         const int row0 = u.pm * 256 + wr * 64 + fr, col0 = u.pn * 256 + wc * 32 + 8 * fq;
; #pragma unroll
;         for (int q = 0; q < 4; ++q) { const int ai = q >> 1, m0 = (q & 1) * 2;
;             u32x4 rw[2][2];
; #pragma unroll
;             for (int mm = 0; mm < 2; ++mm)
; #pragma unroll
;                 for (int bj = 0; bj < 2; ++bj) rw[mm][bj] = *(const u32x4*)(RT + (size_t)(row0 + ai * 128 + (m0 + mm) * 16) * D + col0 + bj * 128);
.LBB0_529:
	v_lshl_add_u32 v134, s14, 8, v229
	v_lshl_or_b32 v224, s12, 8, v231
	v_ashrrev_i32_e32 v225, 31, v224
	v_ashrrev_i32_e32 v135, 31, v134
	v_lshrrev_b32_e32 v136, 5, v224
	v_lshlrev_b32_e32 v136, 10, v136
	v_and_b32_e32 v137, 31, v224
	v_lshl_add_u32 v136, v137, 1, v136
	v_and_b32_e32 v137, 15, v229
	v_lshl_add_u32 v136, v137, 6, v136
	v_add_u32_e32 v136, 0x800, v136
	v_mov_b32_e32 v137, 0
	v_lshl_add_u64 v[136:137], s[6:7], 0, v[136:137]
	v_and_b32_e32 v222, 0xfffffff0, v134
	v_mov_b32_e32 v223, 0
	v_lshlrev_b64 v[222:223], 12, v[222:223]
	v_lshl_add_u64 v[130:131], v[136:137], 0, v[222:223]
	global_load_dwordx4 v[190:193], v[130:131], off offset:-2048
	global_load_dwordx4 v[186:189], v[130:131], off offset:2048
	v_or_b32_e32 v130, 16, v134
	v_and_b32_e32 v130, 0xfffffff0, v130
	v_ashrrev_i32_e32 v131, 31, v130
	v_lshlrev_b64 v[220:221], 12, v[130:131]
	v_lshl_add_u64 v[130:131], v[136:137], 0, v[220:221]
	global_load_dwordx4 v[182:185], v[130:131], off offset:-2048
	s_nop 0
	global_load_dwordx4 v[130:133], v[130:131], off offset:2048
	v_or_b32_e32 v138, 32, v134
	v_and_b32_e32 v138, 0xfffffff0, v138
	v_or_b32_e32 v134, 48, v134
	v_and_b32_e32 v134, 0xfffffff0, v134
	v_ashrrev_i32_e32 v139, 31, v138
	v_ashrrev_i32_e32 v135, 31, v134
	v_lshlrev_b64 v[218:219], 12, v[138:139]
	v_lshlrev_b64 v[216:217], 12, v[134:135]
	v_lshl_add_u64 v[138:139], v[136:137], 0, v[218:219]
	v_lshl_add_u64 v[134:135], v[136:137], 0, v[216:217]
	global_load_dwordx4 v[178:181], v[138:139], off offset:-2048
	global_load_dwordx4 v[174:177], v[138:139], off offset:2048
	global_load_dwordx4 v[170:173], v[134:135], off offset:-2048
	global_load_dwordx4 v[166:169], v[134:135], off offset:2048
	s_mov_b64 s[20:21], 0x80000
	v_lshl_add_u64 v[214:215], v[222:223], 0, s[20:21]
	v_lshl_add_u64 v[134:135], v[136:137], 0, v[214:215]
	v_lshl_add_u64 v[212:213], v[222:223], 0, s[58:59]
	global_load_dwordx4 v[162:165], v[134:135], off offset:-2048
	global_load_dwordx4 v[158:161], v[134:135], off offset:2048
	v_lshl_add_u64 v[134:135], v[136:137], 0, v[212:213]
	global_load_dwordx4 v[154:157], v[134:135], off offset:-2048
	global_load_dwordx4 v[150:153], v[134:135], off offset:2048
	v_lshl_add_u64 v[210:211], v[222:223], 0, s[86:87]
	v_lshl_add_u64 v[134:135], v[136:137], 0, v[210:211]
	v_lshl_add_u64 v[208:209], v[222:223], 0, s[94:95]
	global_load_dwordx4 v[146:149], v[134:135], off offset:-2048
	global_load_dwordx4 v[142:145], v[134:135], off offset:2048
	v_lshl_add_u64 v[134:135], v[136:137], 0, v[208:209]
	global_load_dwordx4 v[138:141], v[134:135], off offset:-2048
	s_nop 0
	global_load_dwordx4 v[134:137], v[134:135], off offset:2048
	v_cndmask_b32_e64 v237, 0, 1, s[4:5]
	v_cmp_ne_u32_e64 s[40:41], 1, v237
	s_andn2_b64 vcc, exec, s[4:5]
	s_cbranch_vccnz .LBB0_531
	s_barrier

; __device__ __forceinline__ unsigned cvt_pk_bf16(float lo, float hi) { unsigned r; asm volatile("v_cvt_pk_bf16_f32 %0, %1, %2" : "=v"(r) : "v"(lo), "v"(hi)); return r; }
; __device__ __forceinline__ float bf_lo(unsigned w) { return __uint_as_float(w << 16); }
; __device__ __forceinline__ float bf_hi(unsigned w) { return __uint_as_float(w & 0xffff0000u); }
;     __device__ __forceinline__ void operator()(const AccT& acc, const Unit& u, int wr, int wc, int fr, int fq) const {
;         const int row0 = u.pm * 256 + wr * 64 + fr, col0 = u.pn * 256 + wc * 32 + 8 * fq;
; #pragma unroll
;         for (int ai = 0; ai < 2; ++ai) {
;             u32x4 gb[4][2];
; #pragma unroll
;             for (int m = 0; m < 4; ++m)
; #pragma unroll
;                 for (int bj = 0; bj < 2; ++bj) gb[m][bj] = __builtin_nontemporal_load((const u32x4*)(GB + (size_t)(row0 + ai * 128 + m * 16) * D + col0 + bj * 128));
; #pragma unroll
;             for (int m = 0; m < 4; ++m)
; #pragma unroll
;                 for (int bj = 0; bj < 2; ++bj) { const u32x4 b = gb[m][bj];
;                     const f32x4 v0 = acc[ai][bj][m][0] * (f32x4){bf_lo(b.x), bf_hi(b.x), bf_lo(b.y), bf_hi(b.y)}, v1 = acc[ai][bj][m][1] * (f32x4){bf_lo(b.z), bf_hi(b.z), bf_lo(b.w), bf_hi(b.w)};
;                     u32x4 w; w.x = cvt_pk_bf16(v0[0], v0[1]); w.y = cvt_pk_bf16(v0[2], v0[3]); w.z = cvt_pk_bf16(v1[0], v1[1]); w.w = cvt_pk_bf16(v1[2], v1[3]);
;                     *(u32x4*)(RT + (size_t)(row0 + ai * 128 + m * 16) * D + col0 + bj * 128) = w; }
;         }
;     }
.LBB0_541:
	v_lshrrev_b32_e32 v134, 5, v224
	v_lshlrev_b32_e32 v134, 10, v134
	v_and_b32_e32 v135, 31, v224
	v_lshl_add_u32 v134, v135, 1, v134
	v_and_b32_e32 v135, 15, v229
	v_lshl_add_u32 v134, v135, 6, v134
	v_add_u32_e32 v134, 0x800, v134
	v_mov_b32_e32 v135, 0
	v_lshl_add_u64 v[136:137], s[8:9], 0, v[134:135]
	v_lshl_add_u64 v[18:19], v[136:137], 0, v[222:223]
	global_load_dwordx4 v[138:141], v[18:19], off offset:-2048 nt
	global_load_dwordx4 v[142:145], v[18:19], off offset:2048 nt
	v_lshl_add_u64 v[18:19], v[136:137], 0, v[220:221]
	global_load_dwordx4 v[146:149], v[18:19], off offset:-2048 nt
	global_load_dwordx4 v[150:153], v[18:19], off offset:2048 nt
	v_lshl_add_u64 v[154:155], v[136:137], 0, v[218:219]
	global_load_dwordx4 v[18:21], v[154:155], off offset:-2048 nt
	v_lshl_add_u64 v[156:157], s[6:7], 0, v[222:223]
	v_lshl_add_u64 v[158:159], s[6:7], 0, v[220:221]
	v_lshl_add_u64 v[162:163], v[136:137], 0, v[216:217]
	v_lshl_add_u64 v[166:167], v[156:157], 0, v[134:135]
	v_lshl_add_u64 v[168:169], v[158:159], 0, v[134:135]
	global_load_dwordx4 v[154:157], v[154:155], off offset:2048 nt
	s_nop 0
	global_load_dwordx4 v[158:161], v[162:163], off offset:-2048 nt
	s_nop 0
	global_load_dwordx4 v[162:165], v[162:163], off offset:2048 nt
	s_andn2_b64 vcc, exec, s[42:43]
	s_mov_b64 s[16:17], -1
	s_waitcnt vmcnt(0)
	v_lshlrev_b32_e32 v170, 16, v138
	v_and_b32_e32 v171, 0xffff0000, v138
	v_lshlrev_b32_e32 v138, 16, v139
	v_and_b32_e32 v139, 0xffff0000, v139
	v_pk_mul_f32 v[94:95], v[94:95], v[170:171]
	v_lshlrev_b32_e32 v172, 16, v140
	v_and_b32_e32 v173, 0xffff0000, v140
	v_lshlrev_b32_e32 v140, 16, v141
	v_and_b32_e32 v141, 0xffff0000, v141
	v_lshlrev_b32_e32 v174, 16, v142
	v_and_b32_e32 v175, 0xffff0000, v142
	v_lshlrev_b32_e32 v142, 16, v143
	v_and_b32_e32 v143, 0xffff0000, v143
	v_pk_mul_f32 v[96:97], v[96:97], v[138:139]
	v_cvt_pk_bf16_f32 v94, v94, v95
	v_lshlrev_b32_e32 v176, 16, v144
	v_cvt_pk_bf16_f32 v95, v96, v97
	v_and_b32_e32 v177, 0xffff0000, v144
	v_lshlrev_b32_e32 v144, 16, v145
	v_and_b32_e32 v145, 0xffff0000, v145
	v_lshlrev_b32_e32 v178, 16, v146
	v_and_b32_e32 v179, 0xffff0000, v146
	v_lshlrev_b32_e32 v146, 16, v147
	v_and_b32_e32 v147, 0xffff0000, v147
	v_pk_mul_f32 v[104:105], v[104:105], v[140:141]
	v_pk_mul_f32 v[102:103], v[102:103], v[172:173]
	v_pk_mul_f32 v[112:113], v[112:113], v[142:143]
	v_pk_mul_f32 v[110:111], v[110:111], v[174:175]
	v_cvt_pk_bf16_f32 v96, v102, v103
	v_cvt_pk_bf16_f32 v97, v104, v105
	global_store_dwordx4 v[166:167], v[94:97], off offset:-2048
	v_lshlrev_b32_e32 v180, 16, v148
	v_and_b32_e32 v181, 0xffff0000, v148
	v_cvt_pk_bf16_f32 v94, v110, v111
	v_cvt_pk_bf16_f32 v95, v112, v113
	v_lshlrev_b32_e32 v148, 16, v149
	v_and_b32_e32 v149, 0xffff0000, v149
	v_lshlrev_b32_e32 v182, 16, v150
	v_and_b32_e32 v183, 0xffff0000, v150
	v_lshlrev_b32_e32 v150, 16, v151
	v_and_b32_e32 v151, 0xffff0000, v151
	v_pk_mul_f32 v[120:121], v[120:121], v[144:145]
	v_pk_mul_f32 v[118:119], v[118:119], v[176:177]
	v_pk_mul_f32 v[124:125], v[124:125], v[146:147]
	v_pk_mul_f32 v[122:123], v[122:123], v[178:179]
	v_cvt_pk_bf16_f32 v96, v118, v119
	v_cvt_pk_bf16_f32 v97, v120, v121
	global_store_dwordx4 v[166:167], v[94:97], off offset:2048
	v_lshlrev_b32_e32 v184, 16, v152
	v_and_b32_e32 v185, 0xffff0000, v152
	v_cvt_pk_bf16_f32 v94, v122, v123
	v_cvt_pk_bf16_f32 v95, v124, v125
	v_lshlrev_b32_e32 v152, 16, v153
	v_and_b32_e32 v153, 0xffff0000, v153
	v_lshlrev_b32_e32 v186, 16, v18
	v_and_b32_e32 v187, 0xffff0000, v18
	v_lshlrev_b32_e32 v18, 16, v19
	v_and_b32_e32 v19, 0xffff0000, v19
	v_pk_mul_f32 v[128:129], v[128:129], v[148:149]
	v_pk_mul_f32 v[126:127], v[126:127], v[180:181]
	v_pk_mul_f32 v[116:117], v[116:117], v[150:151]
	v_pk_mul_f32 v[114:115], v[114:115], v[182:183]
	v_cvt_pk_bf16_f32 v96, v126, v127
	v_cvt_pk_bf16_f32 v97, v128, v129
	global_store_dwordx4 v[168:169], v[94:97], off offset:-2048
	v_pk_mul_f32 v[132:133], v[132:133], v[152:153]
	v_pk_mul_f32 v[130:131], v[130:131], v[184:185]
	v_cvt_pk_bf16_f32 v94, v114, v115
	v_cvt_pk_bf16_f32 v95, v116, v117
	s_nop 0
	v_cvt_pk_bf16_f32 v96, v130, v131
	v_cvt_pk_bf16_f32 v97, v132, v133
	global_store_dwordx4 v[168:169], v[94:97], off offset:2048
	s_nop 1
	v_pk_mul_f32 v[94:95], v[100:101], v[18:19]
	v_pk_mul_f32 v[18:19], v[98:99], v[186:187]
	v_lshlrev_b32_e32 v96, 16, v20
	v_and_b32_e32 v97, 0xffff0000, v20
	v_lshlrev_b32_e32 v20, 16, v21
	v_and_b32_e32 v21, 0xffff0000, v21
	v_cvt_pk_bf16_f32 v18, v18, v19
	v_cvt_pk_bf16_f32 v19, v94, v95
	v_lshl_add_u64 v[94:95], s[6:7], 0, v[218:219]
	v_pk_mul_f32 v[98:99], v[108:109], v[20:21]
	v_pk_mul_f32 v[20:21], v[106:107], v[96:97]
	v_lshl_add_u64 v[94:95], v[94:95], 0, v[134:135]
	v_cvt_pk_bf16_f32 v20, v20, v21
	v_cvt_pk_bf16_f32 v21, v98, v99
	global_store_dwordx4 v[94:95], v[18:21], off offset:-2048
	s_nop 1
	v_lshlrev_b32_e32 v18, 16, v154
	v_and_b32_e32 v19, 0xffff0000, v154
	v_lshlrev_b32_e32 v20, 16, v155
	v_and_b32_e32 v21, 0xffff0000, v155
	v_pk_mul_f32 v[18:19], v[86:87], v[18:19]
	v_pk_mul_f32 v[20:21], v[88:89], v[20:21]
	v_lshlrev_b32_e32 v86, 16, v156
	v_and_b32_e32 v87, 0xffff0000, v156
	v_lshlrev_b32_e32 v88, 16, v157
	v_and_b32_e32 v89, 0xffff0000, v157
	v_cvt_pk_bf16_f32 v18, v18, v19
	v_cvt_pk_bf16_f32 v19, v20, v21
	v_pk_mul_f32 v[88:89], v[92:93], v[88:89]
	v_pk_mul_f32 v[86:87], v[90:91], v[86:87]
	s_nop 0
	v_cvt_pk_bf16_f32 v20, v86, v87
	v_cvt_pk_bf16_f32 v21, v88, v89
	global_store_dwordx4 v[94:95], v[18:21], off offset:2048
	s_nop 1
	v_lshlrev_b32_e32 v18, 16, v158
	v_and_b32_e32 v19, 0xffff0000, v158
	v_lshlrev_b32_e32 v20, 16, v159
	v_and_b32_e32 v21, 0xffff0000, v159
; __device__ __forceinline__ unsigned cvt_pk_bf16(float lo, float hi) { unsigned r; asm volatile("v_cvt_pk_bf16_f32 %0, %1, %2" : "=v"(r) : "v"(lo), "v"(hi)); return r; }
; __device__ __forceinline__ float bf_lo(unsigned w) { return __uint_as_float(w << 16); }
; __device__ __forceinline__ float bf_hi(unsigned w) { return __uint_as_float(w & 0xffff0000u); }
;     __device__ __forceinline__ void operator()(const AccT& acc, const Unit& u, int wr, int wc, int fr, int fq) const {
;     ...
;                 for (int bj = 0; bj < 2; ++bj) gb[m][bj] = __builtin_nontemporal_load((const u32x4*)(GB + (size_t)(row0 + ai * 128 + m * 16) * D + col0 + bj * 128));
; #pragma unroll
;             for (int m = 0; m < 4; ++m)
; #pragma unroll
;                 for (int bj = 0; bj < 2; ++bj) { const u32x4 b = gb[m][bj];
;                     const f32x4 v0 = acc[ai][bj][m][0] * (f32x4){bf_lo(b.x), bf_hi(b.x), bf_lo(b.y), bf_hi(b.y)}, v1 = acc[ai][bj][m][1] * (f32x4){bf_lo(b.z), bf_hi(b.z), bf_lo(b.w), bf_hi(b.w)};
;                     u32x4 w; w.x = cvt_pk_bf16(v0[0], v0[1]); w.y = cvt_pk_bf16(v0[2], v0[3]); w.z = cvt_pk_bf16(v1[0], v1[1]); w.w = cvt_pk_bf16(v1[2], v1[3]);
;                     *(u32x4*)(RT + (size_t)(row0 + ai * 128 + m * 16) * D + col0 + bj * 128) = w; }
	v_pk_mul_f32 v[18:19], v[78:79], v[18:19]
	v_lshlrev_b32_e32 v78, 16, v160
	v_and_b32_e32 v79, 0xffff0000, v160
	v_pk_mul_f32 v[20:21], v[80:81], v[20:21]
	v_pk_mul_f32 v[78:79], v[82:83], v[78:79]
	v_cvt_pk_bf16_f32 v18, v18, v19
	v_cvt_pk_bf16_f32 v19, v20, v21
	v_lshlrev_b32_e32 v80, 16, v161
	v_cvt_pk_bf16_f32 v20, v78, v79
	v_lshl_add_u64 v[78:79], s[6:7], 0, v[216:217]
	v_and_b32_e32 v81, 0xffff0000, v161
	v_lshl_add_u64 v[102:103], v[78:79], 0, v[134:135]
	v_pk_mul_f32 v[80:81], v[84:85], v[80:81]
	s_nop 0
	v_cvt_pk_bf16_f32 v21, v80, v81
	global_store_dwordx4 v[102:103], v[18:21], off offset:-2048
	s_nop 1
	v_lshlrev_b32_e32 v18, 16, v162
	v_and_b32_e32 v19, 0xffff0000, v162
	v_lshlrev_b32_e32 v20, 16, v163
	v_and_b32_e32 v21, 0xffff0000, v163
	v_pk_mul_f32 v[18:19], v[70:71], v[18:19]
	v_lshlrev_b32_e32 v70, 16, v164
	v_and_b32_e32 v71, 0xffff0000, v164
	v_pk_mul_f32 v[20:21], v[72:73], v[20:21]
	v_lshlrev_b32_e32 v72, 16, v165
	v_and_b32_e32 v73, 0xffff0000, v165
	v_pk_mul_f32 v[70:71], v[74:75], v[70:71]
	v_cvt_pk_bf16_f32 v74, v18, v19
	v_lshl_add_u64 v[18:19], v[136:137], 0, v[214:215]
	v_pk_mul_f32 v[72:73], v[76:77], v[72:73]
	v_cvt_pk_bf16_f32 v75, v20, v21
	v_cvt_pk_bf16_f32 v76, v70, v71
	v_lshl_add_u64 v[20:21], v[136:137], 0, v[208:209]
	v_cvt_pk_bf16_f32 v77, v72, v73
	global_load_dwordx4 v[78:81], v[18:19], off offset:-2048 nt
	global_load_dwordx4 v[82:85], v[18:19], off offset:2048 nt
	v_lshl_add_u64 v[18:19], v[136:137], 0, v[212:213]
	global_load_dwordx4 v[86:89], v[18:19], off offset:-2048 nt
	global_load_dwordx4 v[90:93], v[18:19], off offset:2048 nt
	v_lshl_add_u64 v[18:19], v[136:137], 0, v[210:211]
	global_load_dwordx4 v[94:97], v[18:19], off offset:-2048 nt
	global_load_dwordx4 v[98:101], v[18:19], off offset:2048 nt
	global_load_dwordx4 v[70:73], v[20:21], off offset:-2048 nt
	s_nop 0
	global_load_dwordx4 v[18:21], v[20:21], off offset:2048 nt
	s_nop 0
	global_store_dwordx4 v[102:103], v[74:77], off offset:2048
	s_waitcnt vmcnt(8)
	s_nop 0
	v_lshlrev_b32_e32 v74, 16, v78
	v_and_b32_e32 v75, 0xffff0000, v78
	v_lshlrev_b32_e32 v76, 16, v79
	v_and_b32_e32 v77, 0xffff0000, v79
	v_pk_mul_f32 v[62:63], v[62:63], v[74:75]
	v_lshlrev_b32_e32 v74, 16, v80
	v_and_b32_e32 v75, 0xffff0000, v80
	v_pk_mul_f32 v[64:65], v[64:65], v[76:77]
	v_pk_mul_f32 v[66:67], v[66:67], v[74:75]
	v_cvt_pk_bf16_f32 v62, v62, v63
	v_cvt_pk_bf16_f32 v63, v64, v65
	v_lshlrev_b32_e32 v76, 16, v81
	v_cvt_pk_bf16_f32 v64, v66, v67
	v_lshl_add_u64 v[66:67], s[6:7], 0, v[214:215]
	v_and_b32_e32 v77, 0xffff0000, v81
	v_lshl_add_u64 v[66:67], v[66:67], 0, v[134:135]
	v_pk_mul_f32 v[68:69], v[68:69], v[76:77]
	s_nop 0
	v_cvt_pk_bf16_f32 v65, v68, v69
	global_store_dwordx4 v[66:67], v[62:65], off offset:-2048
	s_waitcnt vmcnt(8)
	s_nop 0
	v_lshlrev_b32_e32 v62, 16, v82
	v_and_b32_e32 v63, 0xffff0000, v82
	v_lshlrev_b32_e32 v64, 16, v83
	v_and_b32_e32 v65, 0xffff0000, v83
	v_pk_mul_f32 v[54:55], v[54:55], v[62:63]
	v_pk_mul_f32 v[56:57], v[56:57], v[64:65]
	v_lshlrev_b32_e32 v62, 16, v84
	v_and_b32_e32 v63, 0xffff0000, v84
	v_lshlrev_b32_e32 v64, 16, v85
	v_and_b32_e32 v65, 0xffff0000, v85
	v_cvt_pk_bf16_f32 v54, v54, v55
	v_cvt_pk_bf16_f32 v55, v56, v57
	v_pk_mul_f32 v[60:61], v[60:61], v[64:65]
	v_pk_mul_f32 v[58:59], v[58:59], v[62:63]
	s_nop 0
	v_cvt_pk_bf16_f32 v56, v58, v59
	v_cvt_pk_bf16_f32 v57, v60, v61
	global_store_dwordx4 v[66:67], v[54:57], off offset:2048
	s_waitcnt vmcnt(8)
	s_nop 0
	v_lshlrev_b32_e32 v54, 16, v86
	v_and_b32_e32 v55, 0xffff0000, v86
	v_lshlrev_b32_e32 v56, 16, v87
	v_and_b32_e32 v57, 0xffff0000, v87
	v_pk_mul_f32 v[46:47], v[46:47], v[54:55]
	v_lshlrev_b32_e32 v54, 16, v88
	v_and_b32_e32 v55, 0xffff0000, v88
	v_pk_mul_f32 v[48:49], v[48:49], v[56:57]
	v_pk_mul_f32 v[50:51], v[50:51], v[54:55]
	v_cvt_pk_bf16_f32 v46, v46, v47
	v_cvt_pk_bf16_f32 v47, v48, v49
	v_lshlrev_b32_e32 v56, 16, v89
	v_cvt_pk_bf16_f32 v48, v50, v51
	v_lshl_add_u64 v[50:51], s[6:7], 0, v[212:213]
	v_and_b32_e32 v57, 0xffff0000, v89
	v_lshl_add_u64 v[50:51], v[50:51], 0, v[134:135]
	v_pk_mul_f32 v[52:53], v[52:53], v[56:57]
	s_nop 0
	v_cvt_pk_bf16_f32 v49, v52, v53
	global_store_dwordx4 v[50:51], v[46:49], off offset:-2048
	s_waitcnt vmcnt(8)
; __device__ __forceinline__ unsigned cvt_pk_bf16(float lo, float hi) { unsigned r; asm volatile("v_cvt_pk_bf16_f32 %0, %1, %2" : "=v"(r) : "v"(lo), "v"(hi)); return r; }
; __device__ __forceinline__ float bf_lo(unsigned w) { return __uint_as_float(w << 16); }
; __device__ __forceinline__ float bf_hi(unsigned w) { return __uint_as_float(w & 0xffff0000u); }
;     __device__ __forceinline__ void operator()(const AccT& acc, const Unit& u, int wr, int wc, int fr, int fq) const {
;     ...
;                 for (int bj = 0; bj < 2; ++bj) gb[m][bj] = __builtin_nontemporal_load((const u32x4*)(GB + (size_t)(row0 + ai * 128 + m * 16) * D + col0 + bj * 128));
; #pragma unroll
;             for (int m = 0; m < 4; ++m)
; #pragma unroll
;                 for (int bj = 0; bj < 2; ++bj) { const u32x4 b = gb[m][bj];
;                     const f32x4 v0 = acc[ai][bj][m][0] * (f32x4){bf_lo(b.x), bf_hi(b.x), bf_lo(b.y), bf_hi(b.y)}, v1 = acc[ai][bj][m][1] * (f32x4){bf_lo(b.z), bf_hi(b.z), bf_lo(b.w), bf_hi(b.w)};
;                     u32x4 w; w.x = cvt_pk_bf16(v0[0], v0[1]); w.y = cvt_pk_bf16(v0[2], v0[3]); w.z = cvt_pk_bf16(v1[0], v1[1]); w.w = cvt_pk_bf16(v1[2], v1[3]);
;                     *(u32x4*)(RT + (size_t)(row0 + ai * 128 + m * 16) * D + col0 + bj * 128) = w; }
	s_nop 0
	v_lshlrev_b32_e32 v46, 16, v90
	v_and_b32_e32 v47, 0xffff0000, v90
	v_lshlrev_b32_e32 v48, 16, v91
	v_and_b32_e32 v49, 0xffff0000, v91
	v_pk_mul_f32 v[38:39], v[38:39], v[46:47]
	v_pk_mul_f32 v[40:41], v[40:41], v[48:49]
	v_lshlrev_b32_e32 v46, 16, v92
	v_and_b32_e32 v47, 0xffff0000, v92
	v_lshlrev_b32_e32 v48, 16, v93
	v_and_b32_e32 v49, 0xffff0000, v93
	v_cvt_pk_bf16_f32 v38, v38, v39
	v_cvt_pk_bf16_f32 v39, v40, v41
	v_pk_mul_f32 v[44:45], v[44:45], v[48:49]
	v_pk_mul_f32 v[42:43], v[42:43], v[46:47]
	s_nop 0
	v_cvt_pk_bf16_f32 v40, v42, v43
	v_cvt_pk_bf16_f32 v41, v44, v45
	global_store_dwordx4 v[50:51], v[38:41], off offset:2048
	s_waitcnt vmcnt(8)
	s_nop 0
	v_lshlrev_b32_e32 v38, 16, v94
	v_and_b32_e32 v39, 0xffff0000, v94
	v_lshlrev_b32_e32 v40, 16, v95
	v_and_b32_e32 v41, 0xffff0000, v95
	v_pk_mul_f32 v[30:31], v[30:31], v[38:39]
	v_lshlrev_b32_e32 v38, 16, v96
	v_and_b32_e32 v39, 0xffff0000, v96
	v_pk_mul_f32 v[32:33], v[32:33], v[40:41]
	v_pk_mul_f32 v[34:35], v[34:35], v[38:39]
	v_lshlrev_b32_e32 v40, 16, v97
	v_and_b32_e32 v41, 0xffff0000, v97
	v_cvt_pk_bf16_f32 v30, v30, v31
	v_cvt_pk_bf16_f32 v31, v32, v33
	v_cvt_pk_bf16_f32 v32, v34, v35
	v_lshl_add_u64 v[34:35], s[6:7], 0, v[210:211]
	v_pk_mul_f32 v[36:37], v[36:37], v[40:41]
	v_lshl_add_u64 v[34:35], v[34:35], 0, v[134:135]
	v_cvt_pk_bf16_f32 v33, v36, v37
	global_store_dwordx4 v[34:35], v[30:33], off offset:-2048
	s_waitcnt vmcnt(8)
	s_nop 0
	v_lshlrev_b32_e32 v30, 16, v98
	v_and_b32_e32 v31, 0xffff0000, v98
	v_lshlrev_b32_e32 v32, 16, v99
	v_and_b32_e32 v33, 0xffff0000, v99
	v_pk_mul_f32 v[24:25], v[24:25], v[32:33]
	v_pk_mul_f32 v[22:23], v[22:23], v[30:31]
	v_lshlrev_b32_e32 v30, 16, v100
	v_and_b32_e32 v31, 0xffff0000, v100
	v_lshlrev_b32_e32 v32, 16, v101
	v_and_b32_e32 v33, 0xffff0000, v101
	v_pk_mul_f32 v[28:29], v[28:29], v[32:33]
	v_pk_mul_f32 v[26:27], v[26:27], v[30:31]
	v_cvt_pk_bf16_f32 v22, v22, v23
	v_cvt_pk_bf16_f32 v23, v24, v25
	s_nop 0
	v_cvt_pk_bf16_f32 v24, v26, v27
	v_cvt_pk_bf16_f32 v25, v28, v29
	global_store_dwordx4 v[34:35], v[22:25], off offset:2048
	s_waitcnt vmcnt(8)
	s_nop 0
	v_lshlrev_b32_e32 v22, 16, v70
	v_and_b32_e32 v23, 0xffff0000, v70
	v_lshlrev_b32_e32 v24, 16, v71
	v_and_b32_e32 v25, 0xffff0000, v71
	v_pk_mul_f32 v[16:17], v[16:17], v[24:25]
	v_pk_mul_f32 v[14:15], v[14:15], v[22:23]
	v_lshlrev_b32_e32 v22, 16, v72
	v_and_b32_e32 v23, 0xffff0000, v72
	v_lshlrev_b32_e32 v24, 16, v73
	v_and_b32_e32 v25, 0xffff0000, v73
	v_pk_mul_f32 v[24:25], v[12:13], v[24:25]
	v_pk_mul_f32 v[12:13], v[10:11], v[22:23]
	v_cvt_pk_bf16_f32 v10, v14, v15
	v_lshl_add_u64 v[14:15], s[6:7], 0, v[208:209]
	v_cvt_pk_bf16_f32 v11, v16, v17
	v_cvt_pk_bf16_f32 v12, v12, v13
	v_cvt_pk_bf16_f32 v13, v24, v25
	v_lshl_add_u64 v[14:15], v[14:15], 0, v[134:135]
	global_store_dwordx4 v[14:15], v[10:13], off offset:-2048
	s_waitcnt vmcnt(8)
	s_nop 0
	v_lshlrev_b32_e32 v10, 16, v18
	v_and_b32_e32 v11, 0xffff0000, v18
	v_lshlrev_b32_e32 v12, 16, v19
	v_and_b32_e32 v13, 0xffff0000, v19
	v_pk_mul_f32 v[8:9], v[8:9], v[12:13]
	v_pk_mul_f32 v[6:7], v[6:7], v[10:11]
	v_lshlrev_b32_e32 v10, 16, v20
	v_and_b32_e32 v11, 0xffff0000, v20
	v_lshlrev_b32_e32 v12, 16, v21
	v_and_b32_e32 v13, 0xffff0000, v21
	v_pk_mul_f32 v[12:13], v[4:5], v[12:13]
	v_pk_mul_f32 v[4:5], v[2:3], v[10:11]
	v_cvt_pk_bf16_f32 v2, v6, v7
	v_cvt_pk_bf16_f32 v3, v8, v9
	s_nop 0
	v_cvt_pk_bf16_f32 v4, v4, v5
	v_cvt_pk_bf16_f32 v5, v12, v13
	global_store_dwordx4 v[14:15], v[2:5], off offset:2048
	s_cbranch_vccnz .LBB0_524
	s_and_b64 vcc, exec, s[40:41]
	s_cbranch_vccnz .LBB0_523
	s_barrier
	s_branch .LBB0_523

; #define LAS __attribute__((address_space(3)))
; #define ARGS() KArgs* ap = (KArgs*)__builtin_amdgcn_kernarg_segment_ptr(); asm volatile("" : "+s"(ap)); unsigned char* ws = ap->ws; (void)ws
; __global__ void __launch_bounds__(512, 2) fwd_megakernel(Args a_unused) {
;     ...
;         {
;             ARGS();
;             pg8::Gemm g{(const bf16_t*)(ws + WS_Z) + 5 * SEC, (const bf16_t*)(ws + WS_W + (size_t)l * LW + OW_O), D, D, 0, 0, nullptr, nullptr}; pg8::StaticOrder S; S.init(M, D, G, vcu);
;             bf16_t* R1 = (l + 1 == DEPTH) ? (bf16_t*)(ws + WS_H) : (bf16_t*)ap->out; bf16_t* R2 = (bf16_t*)ap->out + SEC;
;             EpiResid E{(l == 0) ? (const void*)ap->in[0] : (const void*)R2, (void*)R1, (float*)(ws + WS_SSP) + (size_t)(2 * l + 1) * M * 8, l != 0, false, (LAS float*)(lds + 131072 + 1024)};
;             pg8::gemm_phase<EpiResid>(lds, g, S, E, wave_s);
.LBB0_623:
	s_mov_b64 s[100:101], 0x800
	s_mov_b64 s[2:3], s[66:67]
	s_load_dwordx2 s[12:13], s[2:3], 0xa0
	v_readlane_b32 s4, v254, 61
	v_readlane_b32 s5, v254, 62
	s_mov_b64 s[6:7], -1
	s_and_b64 vcc, exec, s[4:5]
	s_cbranch_vccz .LBB0_625
	s_load_dwordx2 s[4:5], s[2:3], 0x98
	s_mov_b64 s[6:7], 0

; #define PG8_STAGE(bufoff, gbase, voff) do { _Pragma("unroll") for (int _i = 0; _i < 2; ++_i) \
;         __builtin_amdgcn_global_load_lds((const unsigned*)((const char*)(gbase) + (voff)[_i]), (LAS unsigned*)(lds + (bufoff) + ldsw + _i * 8192), 16, 0, 0); } while (0)
;     ...
; #pragma unroll
;     for (int i = 0; i < 2; ++i) { int R, C; stage_rc(tid * 16 + i * 8192, R, C); const int Rb = Epi::PERM ? ((R & ~31) + perm32(R & 31)) : R;
;         voffA[i] = (unsigned)(R * lda + C) * 2u; voffB[i] = (unsigned)(Rb * K + C) * 2u; }
;     const size_t kstep = (size_t)(BK * 2);
;     const size_t hstepA = (size_t)HALF * lda * 2, hstepB = (size_t)HALF * K * 2;
;     const size_t tstepA = 2 * hstepA, tstepB = 2 * hstepB;
;     const unsigned ldsw = (unsigned)wid * 1024u;
;     const int aoff = lds_byte(wr * 64 + fr, fq * 8), boff = lds_byte(wc * 32 + fr, fq * 8);
;     ...
;     const char* cA = (const char*)g.A + (size_t)cur.pm * tstepA + (size_t)((cur.pn >> g.ash) * g.amul) * 2; const char* cB = (const char*)g.Bt + (size_t)cur.pn * tstepB;
;     PG8_STAGE(PG8_SB(0, 0), cB, voffB); PG8_STAGE(PG8_SB(0, 1), cB + hstepB, voffB); PG8_STAGE(PG8_SA(0, 0), cA, voffA); PG8_STAGE(PG8_SA(0, 1), cA + hstepA, voffA);
.LBB0_633:
	v_readlane_b32 s2, v254, 56
	s_lshl_b32 s2, s2, 17
	s_and_b64 vcc, exec, s[22:23]
	s_mov_b32 s3, s77
	s_cbranch_vccnz .LBB0_679
	v_ashrrev_i32_e32 v0, 31, v16
	v_lshrrev_b32_e32 v0, 26, v0
	v_add_u32_e32 v0, v16, v0
	v_ashrrev_i32_e32 v10, 6, v0
	v_bfe_i32 v0, v16, 27, 1
	v_lshlrev_b32_e32 v2, 4, v16
	v_lshrrev_b32_e32 v0, 22, v0
	v_add_u32_e32 v0, v2, v0
	v_and_b32_e32 v0, 0xfffffc00, v0
	v_sub_u32_e32 v0, v2, v0
	v_lshrrev_b32_e32 v3, 4, v0
	v_bitop3_b32 v0, v3, v0, 32 bitop3:0x6c
	v_ashrrev_i32_e32 v4, 31, v0
	v_lshrrev_b32_e32 v4, 26, v4
	v_add_u32_e32 v4, v0, v4
	v_lshlrev_b32_e32 v3, 3, v10
	v_ashrrev_i32_e32 v11, 6, v4
	v_and_b32_e32 v4, 0xc0, v4
	v_and_b32_e32 v3, -16, v3
	v_sub_u32_e32 v0, v0, v4
	v_add_u32_e32 v3, v11, v3
	v_ashrrev_i16_sdwa v0, v227, sext(v0) dst_sel:DWORD dst_unused:UNUSED_PAD src0_sel:DWORD src1_sel:BYTE_0
	v_lshlrev_b32_e32 v5, 5, v10
	v_bfe_i32 v12, v0, 0, 16
	v_lshlrev_b32_e32 v0, 1, v3
	v_lshrrev_b32_e32 v4, 2, v3
	v_and_b32_e32 v6, 3, v11
	s_mov_b32 s9, 0xfffe0
	v_and_b32_e32 v5, 32, v5
	v_and_b32_e32 v0, 24, v0
	v_and_b32_e32 v4, 4, v4
	v_and_or_b32 v6, v3, s9, v6
	v_or3_b32 v0, v6, v4, v0
	v_add_lshl_u32 v4, v5, v12, 1
	v_add_u32_e32 v2, 0x2000, v2
	v_lshl_add_u32 v194, v3, 12, v4
	v_lshrrev_b32_e32 v255, 12, v194
	v_and_b32_e32 v250, 0xfff, v194
	v_and_b32_e32 v194, 0xfffffff0, v255
	v_lshlrev_b32_e32 v194, 12, v194
	v_and_b32_e32 v255, 15, v255
	v_lshl_add_u32 v194, v255, 6, v194
	v_and_b32_e32 v255, 64, v250
	v_lshl_add_u32 v194, v255, 4, v194
	v_and_b32_e32 v250, 63, v250
	v_add_u32_e32 v194, v194, v250
	v_ashrrev_i32_e32 v3, 31, v2
	v_lshrrev_b32_e32 v3, 22, v3
	v_add_u32_e32 v3, v2, v3
	v_ashrrev_i32_e32 v13, 10, v3
	v_mul_i32_i24_e32 v3, 0x400, v13
	v_sub_u32_e32 v2, v2, v3
	v_lshrrev_b32_e32 v3, 4, v2
	v_bitop3_b32 v2, v3, v2, 32 bitop3:0x6c
	v_lshl_add_u32 v0, v0, 12, v4
	v_ashrrev_i32_e32 v4, 31, v2
	v_lshrrev_b32_e32 v4, 26, v4
	s_ashr_i32 s14, s16, 6
	v_lshlrev_b32_e32 v3, 3, v13
	v_add_u32_e32 v4, v2, v4
	v_and_b32_e32 v3, -16, v3
	v_ashrrev_i32_e32 v14, 6, v4
	s_ashr_i32 s15, s16, 8
	s_lshl_b32 s25, s14, 10
	v_add_u32_e32 v3, v14, v3
	v_and_b32_e32 v6, 3, v14
	s_waitcnt lgkmcnt(0)
	s_add_u32 s28, s12, 0x26800000
	v_and_or_b32 v6, v3, s9, v6
	s_addc_u32 s29, s13, 0
	v_readlane_b32 s9, v254, 55
	s_add_u32 s9, s12, s9
	s_addc_u32 s10, s13, 0
	s_add_u32 s38, s9, 0x4c00000
	v_and_b32_e32 v4, 0xc0, v4
	s_addc_u32 s39, s10, 0
	s_ashr_i32 s75, s74, 31
	s_ashr_i32 s9, s8, 31
	v_sub_u32_e32 v2, v2, v4
	s_lshl_b64 s[10:11], s[74:75], 20
	s_lshl_b64 s[18:19], s[8:9], 20
	v_ashrrev_i16_sdwa v2, v227, sext(v2) dst_sel:DWORD dst_unused:UNUSED_PAD src0_sel:DWORD src1_sel:BYTE_0
	s_add_u32 s50, s38, s18
	v_lshlrev_b32_e32 v5, 5, v13
	v_bfe_i32 v15, v2, 0, 16
	v_lshlrev_b32_e32 v2, 1, v3
	v_lshrrev_b32_e32 v4, 2, v3
	s_addc_u32 s51, s39, s19
	s_add_i32 s56, s25, 0
	v_and_b32_e32 v5, 32, v5
	v_and_b32_e32 v2, 24, v2
	v_and_b32_e32 v4, 4, v4
	s_add_i32 m0, s56, 0x10000
	v_or3_b32 v2, v6, v4, v2
	v_add_lshl_u32 v4, v5, v15, 1
	global_load_lds_dwordx4 v0, s[50:51]
	s_add_i32 m0, s56, 0x12000
	v_lshl_add_u32 v198, v2, 12, v4
	s_add_u32 s18, s50, 0x80000
	global_load_lds_dwordx4 v198, s[50:51]
	s_addc_u32 s19, s51, 0
	s_add_i32 m0, s56, 0x14000
	v_lshl_add_u32 v196, v3, 12, v4
	v_lshrrev_b32_e32 v255, 12, v196
	v_and_b32_e32 v250, 0xfff, v196
	v_and_b32_e32 v196, 0xfffffff0, v255
	v_lshlrev_b32_e32 v196, 12, v196
	v_and_b32_e32 v255, 15, v255
	v_lshl_add_u32 v196, v255, 6, v196
	v_and_b32_e32 v255, 64, v250
	v_lshl_add_u32 v196, v255, 4, v196
	v_and_b32_e32 v250, 63, v250
	v_add_u32_e32 v196, v196, v250
	global_load_lds_dwordx4 v0, s[18:19]
	s_add_i32 m0, s56, 0x16000
	s_add_u32 s90, s28, s10
	s_addc_u32 s91, s29, s11
	s_add_i32 s57, s56, 0x2000
	global_load_lds_dwordx4 v198, s[18:19]
	s_mov_b32 m0, s56
	s_add_u32 s10, s90, 0x80000
	global_load_lds_dwordx4 v194, s[90:91]
	s_mov_b32 m0, s57
	s_addc_u32 s11, s91, 0
	s_add_i32 s60, s56, 0x4000
	global_load_lds_dwordx4 v196, s[90:91]
	s_mov_b32 m0, s60
	s_add_i32 s61, s56, 0x6000
	global_load_lds_dwordx4 v194, s[10:11]
	s_mov_b32 m0, s61
	v_mov_b32_e32 v199, v1
	global_load_lds_dwordx4 v196, s[10:11]
	v_mov_b32_e32 v195, v1
	v_mov_b32_e32 v197, v1
	s_cmp_eq_u32 s15, 1
	v_lshl_add_u64 v[8:9], s[50:51], 0, v[0:1]
	v_lshl_add_u64 v[6:7], s[50:51], 0, v[198:199]
	v_lshl_add_u64 v[2:3], s[90:91], 0, v[194:195]
	s_cselect_b64 s[10:11], -1, 0
	s_cmp_lg_u32 s15, 1
	v_lshl_add_u64 v[4:5], s[90:91], 0, v[196:197]
	s_cbranch_scc1 .LBB0_636
	s_barrier
; #define PG8_STAGE(bufoff, gbase, voff) do { _Pragma("unroll") for (int _i = 0; _i < 2; ++_i) \
;         __builtin_amdgcn_global_load_lds((const unsigned*)((const char*)(gbase) + (voff)[_i]), (LAS unsigned*)(lds + (bufoff) + ldsw + _i * 8192), 16, 0, 0); } while (0)
; #define PG8_WAIT_V(n) asm volatile("s_waitcnt vmcnt(" #n ")" ::: "memory")
; #define PG8_BAR __builtin_amdgcn_s_barrier()
;     ...
;     for (int i = 0; i < 2; ++i) { int R, C; stage_rc(tid * 16 + i * 8192, R, C); const int Rb = Epi::PERM ? ((R & ~31) + perm32(R & 31)) : R;
;         voffA[i] = (unsigned)(R * lda + C) * 2u; voffB[i] = (unsigned)(Rb * K + C) * 2u; }
;     const size_t kstep = (size_t)(BK * 2);
;     const size_t hstepA = (size_t)HALF * lda * 2, hstepB = (size_t)HALF * K * 2;
;     const size_t tstepA = 2 * hstepA, tstepB = 2 * hstepB;
;     const unsigned ldsw = (unsigned)wid * 1024u;
;     const int aoff = lds_byte(wr * 64 + fr, fq * 8), boff = lds_byte(wc * 32 + fr, fq * 8);
;     ...
;     if (wr == 1) PG8_BAR;
;     PG8_WAIT_V(2); PG8_BAR;
;     PG8_STAGE(PG8_SB(1, 0), cB + kstep, voffB); PG8_STAGE(PG8_SA(1, 0), cA + kstep, voffA); PG8_STAGE(PG8_SB(1, 1), cB + hstepB + kstep, voffB);
;     PG8_WAIT_V(6); PG8_BAR;
.LBB0_636:
	s_lshl_b64 s[18:19], s[2:3], 2
	s_add_u32 s9, s12, s18
	s_addc_u32 s13, s13, s19
	v_bfe_u32 v17, v16, 4, 2
	s_add_u32 s12, s9, 0x36c00000
	v_and_b32_e32 v18, 15, v16
	v_lshlrev_b32_e32 v20, 4, v17
	v_lshlrev_b32_e32 v16, 2, v16
	s_addc_u32 s13, s13, 0
	s_and_b32 s9, s14, 3
	v_lshl_or_b32 v21, v18, 6, v20
	s_lshl_b32 s14, s15, 13
	v_and_b32_e32 v16, 32, v16
	s_add_i32 m0, s56, 0x18000
	v_lshl_add_u64 v[8:9], v[8:9], 0, s[34:35]
	v_bitop3_b32 v22, v21, s14, v16 bitop3:0xde
	s_lshl_b32 s14, s9, 12
	s_waitcnt vmcnt(2)
	s_barrier
	global_load_lds_dwordx4 v[8:9], off
	v_lshl_add_u64 v[6:7], v[6:7], 0, s[34:35]
	s_add_i32 m0, s56, 0x1a000
	s_add_i32 s75, s56, 0x8000
	s_add_i32 s76, s56, 0xa000
	v_bitop3_b32 v225, v21, s14, v16 bitop3:0xde
	global_load_lds_dwordx4 v[6:7], off
	v_lshl_add_u64 v[2:3], v[2:3], 0, s[100:101]
	s_mov_b32 m0, s75
	s_add_u32 s14, s50, 0x80080
	v_lshl_or_b32 v224, s15, 6, v18
	global_load_lds_dwordx4 v[2:3], off
	v_lshl_add_u64 v[2:3], v[4:5], 0, s[100:101]
	s_mov_b32 m0, s76
	s_addc_u32 s15, s51, 0
	global_load_lds_dwordx4 v[2:3], off
	s_add_i32 m0, s56, 0x1c000
	v_lshl_add_u64 v[2:3], s[14:15], 0, v[0:1]
	global_load_lds_dwordx4 v[2:3], off
	v_lshl_add_u64 v[2:3], s[14:15], 0, v[198:199]
	s_add_i32 m0, s56, 0x1e000
	s_cmpk_lt_u32 s16, 0x100
	global_load_lds_dwordx4 v[2:3], off
	s_cselect_b64 s[14:15], -1, 0
	s_and_b32 s16, s16, 0xffffff00
	s_lshl_b32 s17, s9, 6
	v_lshlrev_b32_e32 v3, 15, v10
	s_or_b32 s16, s17, s16
	v_and_b32_e32 v3, 0xffff0000, v3
	v_or3_b32 v230, s16, v20, v18
	s_movk_i32 s16, 0x100
	v_lshl_add_u32 v3, v11, 12, v3
	v_and_b32_e32 v4, 1, v10
	v_cmp_gt_i32_e64 s[42:43], s16, v230
	v_readlane_b32 s16, v254, 57
	v_lshl_or_b32 v3, v4, 6, v3
	v_lshlrev_b32_e32 v19, 3, v17
	v_readlane_b32 s17, v254, 58
	s_bitcmp1_b32 s16, 0
	v_lshl_add_u32 v200, v12, 1, v3
	v_lshrrev_b32_e32 v255, 12, v200
	v_and_b32_e32 v250, 0xfff, v200
	v_and_b32_e32 v200, 0xfffffff0, v255
	v_lshlrev_b32_e32 v200, 12, v200
	v_and_b32_e32 v255, 15, v255
	v_lshl_add_u32 v200, v255, 6, v200
	v_and_b32_e32 v255, 64, v250
	v_lshl_add_u32 v200, v255, 4, v200
	v_and_b32_e32 v250, 63, v250
	v_add_u32_e32 v200, v200, v250
	v_lshlrev_b32_e32 v3, 15, v13
	v_lshl_or_b32 v229, s9, 5, v19
	s_cselect_b64 s[16:17], -1, 0
	s_lshl_b32 s9, s9, 2
	v_and_b32_e32 v3, 0xffff0000, v3
	s_waitcnt vmcnt(6)
	v_lshlrev_b32_e32 v2, 4, v230
	s_add_i32 s9, s9, 0
	v_lshl_add_u32 v3, v14, 12, v3
	v_and_b32_e32 v4, 1, v13
	s_add_i32 s9, s9, 0x20400
	v_lshl_or_b32 v3, v4, 6, v3
	v_add_u32_e32 v2, 0, v2
	s_mov_b32 s77, 0
	v_cmp_eq_u32_e64 s[40:41], 0, v17
	s_xor_b64 s[16:17], s[16:17], -1
	v_lshl_add_u32 v231, v224, 4, s9
	v_mov_b32_e32 v201, v1
	v_lshl_add_u32 v202, v15, 1, v3
	v_lshrrev_b32_e32 v255, 12, v202
	v_and_b32_e32 v250, 0xfff, v202
	v_and_b32_e32 v202, 0xfffffff0, v255
	v_lshlrev_b32_e32 v202, 12, v202
	v_and_b32_e32 v255, 15, v255
	v_lshl_add_u32 v202, v255, 6, v202
	v_and_b32_e32 v255, 64, v250
	v_lshl_add_u32 v202, v255, 4, v202
	v_and_b32_e32 v250, 63, v250
	v_add_u32_e32 v202, v202, v250
	v_mov_b32_e32 v203, v1
	v_add_u32_e32 v232, 0, v22
	v_add_u32_e32 v233, 0x20400, v2
	s_barrier
	s_branch .LBB0_639

; #define PG8_BAR __builtin_amdgcn_s_barrier()
;     ...
;         const char* nA = has_next ? (const char*)g.A + (size_t)nxt.pm * tstepA + (size_t)((nxt.pn >> g.ash) * g.amul) * 2 : cA; const char* nB = has_next ? (const char*)g.Bt + (size_t)nxt.pn * tstepB : cB;
;         PG8_KLOOP();
;         if (wr == 0) PG8_BAR;
;         E(acc, cur, wr, wc, fr, fq);
;         if (!has_next) break;
; #pragma unroll
;         for (int a = 0; a < 2; ++a)
; #pragma unroll
;             for (int b = 0; b < 2; ++b)
; #pragma unroll
;                 for (int m = 0; m < 4; ++m)
; #pragma unroll
;                     for (int n = 0; n < 2; ++n) acc[a][b][m][n] = (f32x4){0.f, 0.f, 0.f, 0.f};
;         cur = nxt; cA = nA; cB = nB; ++ui;
.LBB0_645:
	s_ashr_i32 s21, s20, 31
	s_lshl_b64 s[22:23], s[20:21], 20
	s_add_u32 s48, s28, s22
	s_addc_u32 s49, s29, s23
	s_and_b64 s[22:23], s[44:45], exec
	s_cselect_b32 s9, s49, s91
	s_cselect_b32 s21, s48, s90
	s_ashr_i32 s19, s18, 31
	s_lshl_b64 s[22:23], s[18:19], 20
	s_add_u32 s62, s38, s22
	s_addc_u32 s63, s39, s23
	s_and_b64 s[22:23], s[44:45], exec
	s_cselect_b32 s19, s63, s51
	s_cselect_b32 s36, s62, s50
	s_add_u32 s90, s90, 0x80800
	s_addc_u32 s91, s91, 0
	s_add_u32 s37, s50, 0x100
	v_mov_b32_e32 v2, 0
	s_addc_u32 s46, s51, 0
	s_mov_b32 s47, -2
	v_mov_b32_e32 v3, v2
	v_mov_b32_e32 v4, v2
	v_mov_b32_e32 v5, v2
	v_mov_b32_e32 v6, v2
	v_mov_b32_e32 v7, v2
	v_mov_b32_e32 v8, v2
	v_mov_b32_e32 v9, v2
	v_mov_b32_e32 v18, v2
	v_mov_b32_e32 v19, v2
	v_mov_b32_e32 v20, v2
	v_mov_b32_e32 v21, v2
	v_mov_b32_e32 v22, v2
	v_mov_b32_e32 v23, v2
	v_mov_b32_e32 v24, v2
	v_mov_b32_e32 v25, v2
	v_mov_b32_e32 v34, v2
	v_mov_b32_e32 v35, v2
	v_mov_b32_e32 v36, v2
	v_mov_b32_e32 v37, v2
	v_mov_b32_e32 v38, v2
	v_mov_b32_e32 v39, v2
	v_mov_b32_e32 v40, v2
	v_mov_b32_e32 v41, v2
	v_mov_b32_e32 v50, v2
	v_mov_b32_e32 v51, v2
	v_mov_b32_e32 v52, v2
	v_mov_b32_e32 v53, v2
	v_mov_b32_e32 v54, v2
	v_mov_b32_e32 v55, v2
	v_mov_b32_e32 v56, v2
	v_mov_b32_e32 v57, v2
	v_mov_b32_e32 v10, v2
	v_mov_b32_e32 v11, v2
	v_mov_b32_e32 v12, v2
	v_mov_b32_e32 v13, v2
	v_mov_b32_e32 v14, v2
	v_mov_b32_e32 v15, v2
	v_mov_b32_e32 v16, v2
	v_mov_b32_e32 v17, v2
	v_mov_b32_e32 v26, v2
	v_mov_b32_e32 v27, v2
	v_mov_b32_e32 v28, v2
	v_mov_b32_e32 v29, v2
	v_mov_b32_e32 v30, v2
	v_mov_b32_e32 v31, v2
	v_mov_b32_e32 v32, v2
	v_mov_b32_e32 v33, v2
	v_mov_b32_e32 v42, v2
	v_mov_b32_e32 v43, v2
	v_mov_b32_e32 v44, v2
	v_mov_b32_e32 v45, v2
	v_mov_b32_e32 v46, v2
	v_mov_b32_e32 v47, v2
	v_mov_b32_e32 v48, v2
	v_mov_b32_e32 v49, v2
	v_mov_b32_e32 v58, v2
	v_mov_b32_e32 v59, v2
	v_mov_b32_e32 v60, v2
	v_mov_b32_e32 v61, v2
	v_mov_b32_e32 v62, v2
	v_mov_b32_e32 v63, v2
	v_mov_b32_e32 v64, v2
	v_mov_b32_e32 v65, v2
	v_mov_b32_e32 v66, v2
	v_mov_b32_e32 v67, v2
	v_mov_b32_e32 v68, v2
	v_mov_b32_e32 v69, v2
	v_mov_b32_e32 v70, v2
	v_mov_b32_e32 v71, v2
	v_mov_b32_e32 v72, v2
	v_mov_b32_e32 v73, v2
	v_mov_b32_e32 v82, v2
	v_mov_b32_e32 v83, v2
	v_mov_b32_e32 v84, v2
	v_mov_b32_e32 v85, v2
	v_mov_b32_e32 v86, v2
	v_mov_b32_e32 v87, v2
	v_mov_b32_e32 v88, v2
	v_mov_b32_e32 v89, v2
	v_mov_b32_e32 v98, v2
	v_mov_b32_e32 v99, v2
	v_mov_b32_e32 v100, v2
	v_mov_b32_e32 v101, v2
	v_mov_b32_e32 v102, v2
	v_mov_b32_e32 v103, v2
	v_mov_b32_e32 v104, v2
	v_mov_b32_e32 v105, v2
	v_mov_b32_e32 v114, v2
	v_mov_b32_e32 v115, v2
	v_mov_b32_e32 v116, v2
	v_mov_b32_e32 v117, v2
	v_mov_b32_e32 v118, v2
	v_mov_b32_e32 v119, v2
	v_mov_b32_e32 v120, v2
	v_mov_b32_e32 v121, v2
	v_mov_b32_e32 v74, v2
	v_mov_b32_e32 v75, v2
	v_mov_b32_e32 v76, v2
	v_mov_b32_e32 v77, v2
	v_mov_b32_e32 v78, v2
	v_mov_b32_e32 v79, v2
	v_mov_b32_e32 v80, v2
	v_mov_b32_e32 v81, v2
	v_mov_b32_e32 v90, v2
	v_mov_b32_e32 v91, v2
	v_mov_b32_e32 v92, v2
	v_mov_b32_e32 v93, v2
	v_mov_b32_e32 v94, v2
	v_mov_b32_e32 v95, v2
	v_mov_b32_e32 v96, v2
	v_mov_b32_e32 v97, v2
	v_mov_b32_e32 v106, v2
	v_mov_b32_e32 v107, v2
	v_mov_b32_e32 v108, v2
	v_mov_b32_e32 v109, v2
	v_mov_b32_e32 v110, v2
	v_mov_b32_e32 v111, v2
	v_mov_b32_e32 v112, v2
	v_mov_b32_e32 v113, v2
	v_mov_b32_e32 v122, v2
	v_mov_b32_e32 v123, v2
	v_mov_b32_e32 v124, v2
	v_mov_b32_e32 v125, v2
	v_mov_b32_e32 v126, v2
	v_mov_b32_e32 v127, v2
	v_mov_b32_e32 v128, v2
	v_mov_b32_e32 v129, v2
.LBB0_646:
	s_add_u32 s22, s90, 0xfff80800
	s_addc_u32 s23, s91, -1
	s_add_i32 s24, 0, 0x10000
	s_cmp_eq_u32 s47, 28
	s_cselect_b32 s23, s9, s23
	s_cselect_b32 s22, s21, s22
	s_cselect_b32 s27, s19, s46
	s_cselect_b32 s26, s36, s37
	s_add_i32 s64, 0, 0x14000
	v_add_u32_e32 v142, s24, v225
	v_add_u32_e32 v158, s64, v225
	ds_read_b128 v[130:133], v142
	ds_read_b128 v[134:137], v142 offset:1024
	ds_read_b128 v[138:141], v142 offset:2048
	ds_read_b128 v[142:145], v142 offset:3072
	ds_read_b128 v[146:149], v158
	ds_read_b128 v[150:153], v158 offset:1024
	ds_read_b128 v[154:157], v158 offset:2048
	ds_read_b128 v[158:161], v158 offset:3072
	v_lshl_add_u64 v[204:205], s[90:91], 0, v[200:201]
	s_add_i32 m0, s56, 0xc000
	ds_read_b128 v[162:165], v232
	ds_read_b128 v[166:169], v232 offset:1024
	ds_read_b128 v[170:173], v232 offset:2048
	ds_read_b128 v[174:177], v232 offset:3072
	ds_read_b128 v[178:181], v232 offset:4096
	ds_read_b128 v[182:185], v232 offset:5120
	ds_read_b128 v[186:189], v232 offset:6144
	ds_read_b128 v[190:193], v232 offset:7168
	global_load_lds_dwordx4 v[204:205], off
	v_lshl_add_u64 v[204:205], s[90:91], 0, v[202:203]
	s_add_i32 m0, s56, 0xe000
	s_nop 0
	global_load_lds_dwordx4 v[204:205], off
	s_waitcnt vmcnt(8)
	s_waitcnt lgkmcnt(0)
	s_setprio 1
	s_barrier
	v_mfma_f32_16x16x32_bf16 v[126:129], v[130:133], v[162:165], v[126:129]
	v_mfma_f32_16x16x32_bf16 v[122:125], v[138:141], v[162:165], v[122:125]
	v_mfma_f32_16x16x32_bf16 v[110:113], v[130:133], v[170:173], v[110:113]
	v_mfma_f32_16x16x32_bf16 v[106:109], v[138:141], v[170:173], v[106:109]
	v_mfma_f32_16x16x32_bf16 v[94:97], v[130:133], v[178:181], v[94:97]
	v_mfma_f32_16x16x32_bf16 v[90:93], v[138:141], v[178:181], v[90:93]
	v_mfma_f32_16x16x32_bf16 v[78:81], v[130:133], v[186:189], v[78:81]
	v_mfma_f32_16x16x32_bf16 v[74:77], v[138:141], v[186:189], v[74:77]
	v_mfma_f32_16x16x32_bf16 v[126:129], v[134:137], v[166:169], v[126:129]
	v_mfma_f32_16x16x32_bf16 v[122:125], v[142:145], v[166:169], v[122:125]
	v_mfma_f32_16x16x32_bf16 v[110:113], v[134:137], v[174:177], v[110:113]
	v_mfma_f32_16x16x32_bf16 v[106:109], v[142:145], v[174:177], v[106:109]
	v_mfma_f32_16x16x32_bf16 v[94:97], v[134:137], v[182:185], v[94:97]
	v_mfma_f32_16x16x32_bf16 v[90:93], v[142:145], v[182:185], v[90:93]
	v_mfma_f32_16x16x32_bf16 v[78:81], v[134:137], v[190:193], v[78:81]
	v_mfma_f32_16x16x32_bf16 v[74:77], v[142:145], v[190:193], v[74:77]
	s_setprio 0
	s_setprio 1
	v_mfma_f32_16x16x32_bf16 v[118:121], v[146:149], v[162:165], v[118:121]
	v_mfma_f32_16x16x32_bf16 v[114:117], v[154:157], v[162:165], v[114:117]
	v_mfma_f32_16x16x32_bf16 v[102:105], v[146:149], v[170:173], v[102:105]
	v_mfma_f32_16x16x32_bf16 v[98:101], v[154:157], v[170:173], v[98:101]
	v_mfma_f32_16x16x32_bf16 v[86:89], v[146:149], v[178:181], v[86:89]
	v_mfma_f32_16x16x32_bf16 v[82:85], v[154:157], v[178:181], v[82:85]
	v_mfma_f32_16x16x32_bf16 v[70:73], v[146:149], v[186:189], v[70:73]
	v_mfma_f32_16x16x32_bf16 v[66:69], v[154:157], v[186:189], v[66:69]
	v_mfma_f32_16x16x32_bf16 v[118:121], v[150:153], v[166:169], v[118:121]
	v_mfma_f32_16x16x32_bf16 v[114:117], v[158:161], v[166:169], v[114:117]
	v_mfma_f32_16x16x32_bf16 v[102:105], v[150:153], v[174:177], v[102:105]
	v_mfma_f32_16x16x32_bf16 v[98:101], v[158:161], v[174:177], v[98:101]
	v_mfma_f32_16x16x32_bf16 v[86:89], v[150:153], v[182:185], v[86:89]
	v_mfma_f32_16x16x32_bf16 v[82:85], v[158:161], v[182:185], v[82:85]
	v_mfma_f32_16x16x32_bf16 v[70:73], v[150:153], v[190:193], v[70:73]
	v_mfma_f32_16x16x32_bf16 v[66:69], v[158:161], v[190:193], v[66:69]
	s_barrier
	s_setprio 0
	s_add_i32 s24, s24, s25
	v_lshl_add_u64 v[204:205], s[26:27], 0, v[0:1]
	s_mov_b32 m0, s24
	ds_read_b128 v[162:165], v232 offset:16384
	ds_read_b128 v[166:169], v232 offset:17408
	ds_read_b128 v[170:173], v232 offset:18432
	ds_read_b128 v[174:177], v232 offset:19456
	ds_read_b128 v[178:181], v232 offset:20480
	ds_read_b128 v[182:185], v232 offset:21504
	ds_read_b128 v[186:189], v232 offset:22528
	ds_read_b128 v[190:193], v232 offset:23552
	global_load_lds_dwordx4 v[204:205], off
	s_add_i32 m0, s24, 0x2000
	s_add_u32 s50, s26, 0x80000
	v_lshl_add_u64 v[206:207], s[26:27], 0, v[198:199]
	s_addc_u32 s51, s27, 0
	s_add_i32 s24, s64, s25
	global_load_lds_dwordx4 v[206:207], off
	v_lshl_add_u64 v[208:209], s[50:51], 0, v[0:1]
	s_mov_b32 m0, s24
	v_lshl_add_u64 v[210:211], s[22:23], 0, v[196:197]
	global_load_lds_dwordx4 v[208:209], off
	v_lshl_add_u64 v[208:209], s[50:51], 0, v[198:199]
	s_add_i32 m0, s24, 0x2000
	s_nop 0
	global_load_lds_dwordx4 v[208:209], off
	v_lshl_add_u64 v[208:209], s[22:23], 0, v[194:195]
	s_mov_b32 m0, s56
	s_nop 0
	global_load_lds_dwordx4 v[208:209], off
	s_mov_b32 m0, s57
	s_nop 0
	global_load_lds_dwordx4 v[210:211], off
	s_waitcnt vmcnt(8)
	s_waitcnt lgkmcnt(0)
	s_setprio 1
	s_barrier
	v_mfma_f32_16x16x32_bf16 v[62:65], v[130:133], v[162:165], v[62:65]
	v_mfma_f32_16x16x32_bf16 v[58:61], v[138:141], v[162:165], v[58:61]
	v_mfma_f32_16x16x32_bf16 v[46:49], v[130:133], v[170:173], v[46:49]
	v_mfma_f32_16x16x32_bf16 v[42:45], v[138:141], v[170:173], v[42:45]
	v_mfma_f32_16x16x32_bf16 v[30:33], v[130:133], v[178:181], v[30:33]
	v_mfma_f32_16x16x32_bf16 v[26:29], v[138:141], v[178:181], v[26:29]
	v_mfma_f32_16x16x32_bf16 v[14:17], v[130:133], v[186:189], v[14:17]
	v_mfma_f32_16x16x32_bf16 v[10:13], v[138:141], v[186:189], v[10:13]
	v_mfma_f32_16x16x32_bf16 v[62:65], v[134:137], v[166:169], v[62:65]
	v_mfma_f32_16x16x32_bf16 v[58:61], v[142:145], v[166:169], v[58:61]
	v_mfma_f32_16x16x32_bf16 v[46:49], v[134:137], v[174:177], v[46:49]
	v_mfma_f32_16x16x32_bf16 v[42:45], v[142:145], v[174:177], v[42:45]
	v_mfma_f32_16x16x32_bf16 v[30:33], v[134:137], v[182:185], v[30:33]
	v_mfma_f32_16x16x32_bf16 v[26:29], v[142:145], v[182:185], v[26:29]
	v_mfma_f32_16x16x32_bf16 v[14:17], v[134:137], v[190:193], v[14:17]
	v_mfma_f32_16x16x32_bf16 v[10:13], v[142:145], v[190:193], v[10:13]
	s_setprio 0
	s_setprio 1
	v_mfma_f32_16x16x32_bf16 v[54:57], v[146:149], v[162:165], v[54:57]
	v_mfma_f32_16x16x32_bf16 v[50:53], v[154:157], v[162:165], v[50:53]
	v_mfma_f32_16x16x32_bf16 v[38:41], v[146:149], v[170:173], v[38:41]
	v_mfma_f32_16x16x32_bf16 v[34:37], v[154:157], v[170:173], v[34:37]
	v_mfma_f32_16x16x32_bf16 v[22:25], v[146:149], v[178:181], v[22:25]
	v_mfma_f32_16x16x32_bf16 v[18:21], v[154:157], v[178:181], v[18:21]
	v_mfma_f32_16x16x32_bf16 v[6:9], v[146:149], v[186:189], v[6:9]
	v_mfma_f32_16x16x32_bf16 v[2:5], v[154:157], v[186:189], v[2:5]
	v_mfma_f32_16x16x32_bf16 v[54:57], v[150:153], v[166:169], v[54:57]
	v_mfma_f32_16x16x32_bf16 v[50:53], v[158:161], v[166:169], v[50:53]
	v_mfma_f32_16x16x32_bf16 v[38:41], v[150:153], v[174:177], v[38:41]
	v_mfma_f32_16x16x32_bf16 v[34:37], v[158:161], v[174:177], v[34:37]
	v_mfma_f32_16x16x32_bf16 v[22:25], v[150:153], v[182:185], v[22:25]
	v_mfma_f32_16x16x32_bf16 v[18:21], v[158:161], v[182:185], v[18:21]
	v_mfma_f32_16x16x32_bf16 v[6:9], v[150:153], v[190:193], v[6:9]
	v_mfma_f32_16x16x32_bf16 v[2:5], v[158:161], v[190:193], v[2:5]
	s_barrier
	s_setprio 0
	s_add_i32 s24, 0, 0x18000
	s_add_i32 s50, 0, 0x1c000
	v_add_u32_e32 v142, s24, v225
	v_add_u32_e32 v158, s50, v225
	ds_read_b128 v[130:133], v142
	ds_read_b128 v[134:137], v142 offset:1024
	ds_read_b128 v[138:141], v142 offset:2048
	ds_read_b128 v[142:145], v142 offset:3072
	ds_read_b128 v[146:149], v158
	ds_read_b128 v[150:153], v158 offset:1024
	ds_read_b128 v[154:157], v158 offset:2048
	ds_read_b128 v[158:161], v158 offset:3072
	s_add_u32 s22, s22, 0x80000
	s_addc_u32 s23, s23, 0
	s_mov_b32 m0, s60
	v_lshl_add_u64 v[212:213], s[22:23], 0, v[194:195]
	ds_read_b128 v[162:165], v232 offset:32768
	ds_read_b128 v[166:169], v232 offset:33792
	ds_read_b128 v[170:173], v232 offset:34816
	ds_read_b128 v[174:177], v232 offset:35840
	ds_read_b128 v[178:181], v232 offset:36864
	ds_read_b128 v[182:185], v232 offset:37888
	ds_read_b128 v[186:189], v232 offset:38912
	ds_read_b128 v[190:193], v232 offset:39936
	global_load_lds_dwordx4 v[212:213], off
	v_lshl_add_u64 v[212:213], s[22:23], 0, v[196:197]
	s_mov_b32 m0, s61
	s_nop 0
	global_load_lds_dwordx4 v[212:213], off
	s_waitcnt vmcnt(8)
	s_waitcnt lgkmcnt(0)
	s_setprio 1
	s_barrier
	v_mfma_f32_16x16x32_bf16 v[126:129], v[130:133], v[162:165], v[126:129]
	v_mfma_f32_16x16x32_bf16 v[122:125], v[138:141], v[162:165], v[122:125]
	v_mfma_f32_16x16x32_bf16 v[110:113], v[130:133], v[170:173], v[110:113]
	v_mfma_f32_16x16x32_bf16 v[106:109], v[138:141], v[170:173], v[106:109]
	v_mfma_f32_16x16x32_bf16 v[94:97], v[130:133], v[178:181], v[94:97]
	v_mfma_f32_16x16x32_bf16 v[90:93], v[138:141], v[178:181], v[90:93]
	v_mfma_f32_16x16x32_bf16 v[78:81], v[130:133], v[186:189], v[78:81]
	v_mfma_f32_16x16x32_bf16 v[74:77], v[138:141], v[186:189], v[74:77]
	v_mfma_f32_16x16x32_bf16 v[126:129], v[134:137], v[166:169], v[126:129]
	v_mfma_f32_16x16x32_bf16 v[122:125], v[142:145], v[166:169], v[122:125]
	v_mfma_f32_16x16x32_bf16 v[110:113], v[134:137], v[174:177], v[110:113]
	v_mfma_f32_16x16x32_bf16 v[106:109], v[142:145], v[174:177], v[106:109]
	v_mfma_f32_16x16x32_bf16 v[94:97], v[134:137], v[182:185], v[94:97]
	v_mfma_f32_16x16x32_bf16 v[90:93], v[142:145], v[182:185], v[90:93]
	v_mfma_f32_16x16x32_bf16 v[78:81], v[134:137], v[190:193], v[78:81]
	v_mfma_f32_16x16x32_bf16 v[74:77], v[142:145], v[190:193], v[74:77]
	s_setprio 0
	s_setprio 1
	v_mfma_f32_16x16x32_bf16 v[118:121], v[146:149], v[162:165], v[118:121]
	v_mfma_f32_16x16x32_bf16 v[114:117], v[154:157], v[162:165], v[114:117]
	v_mfma_f32_16x16x32_bf16 v[102:105], v[146:149], v[170:173], v[102:105]
	v_mfma_f32_16x16x32_bf16 v[98:101], v[154:157], v[170:173], v[98:101]
	v_mfma_f32_16x16x32_bf16 v[86:89], v[146:149], v[178:181], v[86:89]
	v_mfma_f32_16x16x32_bf16 v[82:85], v[154:157], v[178:181], v[82:85]
	v_mfma_f32_16x16x32_bf16 v[70:73], v[146:149], v[186:189], v[70:73]
	v_mfma_f32_16x16x32_bf16 v[66:69], v[154:157], v[186:189], v[66:69]
	v_mfma_f32_16x16x32_bf16 v[118:121], v[150:153], v[166:169], v[118:121]
	v_mfma_f32_16x16x32_bf16 v[114:117], v[158:161], v[166:169], v[114:117]
	v_mfma_f32_16x16x32_bf16 v[102:105], v[150:153], v[174:177], v[102:105]
	v_mfma_f32_16x16x32_bf16 v[98:101], v[158:161], v[174:177], v[98:101]
	v_mfma_f32_16x16x32_bf16 v[86:89], v[150:153], v[182:185], v[86:89]
	v_mfma_f32_16x16x32_bf16 v[82:85], v[158:161], v[182:185], v[82:85]
	v_mfma_f32_16x16x32_bf16 v[70:73], v[150:153], v[190:193], v[70:73]
	v_mfma_f32_16x16x32_bf16 v[66:69], v[158:161], v[190:193], v[66:69]
	s_barrier
	s_setprio 0
	s_add_i32 s22, s24, s25
	v_lshl_add_u64 v[204:205], v[204:205], 0, s[34:35]
	s_mov_b32 m0, s22
	ds_read_b128 v[162:165], v232 offset:49152
	ds_read_b128 v[166:169], v232 offset:50176
	ds_read_b128 v[170:173], v232 offset:51200
	ds_read_b128 v[174:177], v232 offset:52224
	ds_read_b128 v[178:181], v232 offset:53248
	ds_read_b128 v[182:185], v232 offset:54272
	ds_read_b128 v[186:189], v232 offset:55296
	ds_read_b128 v[190:193], v232 offset:56320
	global_load_lds_dwordx4 v[204:205], off
	s_add_i32 m0, s22, 0x2000
	s_add_u32 s22, s26, 0x80080
	v_lshl_add_u64 v[204:205], v[206:207], 0, s[34:35]
	s_addc_u32 s23, s27, 0
	s_add_i32 s24, s50, s25
	global_load_lds_dwordx4 v[204:205], off
	v_lshl_add_u64 v[204:205], s[22:23], 0, v[0:1]
	s_mov_b32 m0, s24
	s_nop 0
	global_load_lds_dwordx4 v[204:205], off
	v_lshl_add_u64 v[204:205], s[22:23], 0, v[198:199]
	s_add_i32 m0, s24, 0x2000
	s_nop 0
	global_load_lds_dwordx4 v[204:205], off
	v_lshl_add_u64 v[204:205], v[208:209], 0, s[100:101]
	s_mov_b32 m0, s75
	s_nop 0
	global_load_lds_dwordx4 v[204:205], off
	v_lshl_add_u64 v[204:205], v[210:211], 0, s[100:101]
	s_mov_b32 m0, s76
	s_nop 0
	global_load_lds_dwordx4 v[204:205], off
	s_waitcnt vmcnt(8)
	s_waitcnt lgkmcnt(0)
	s_setprio 1
	s_barrier
	v_mfma_f32_16x16x32_bf16 v[62:65], v[130:133], v[162:165], v[62:65]
	v_mfma_f32_16x16x32_bf16 v[58:61], v[138:141], v[162:165], v[58:61]
	v_mfma_f32_16x16x32_bf16 v[46:49], v[130:133], v[170:173], v[46:49]
	v_mfma_f32_16x16x32_bf16 v[42:45], v[138:141], v[170:173], v[42:45]
	v_mfma_f32_16x16x32_bf16 v[30:33], v[130:133], v[178:181], v[30:33]
	v_mfma_f32_16x16x32_bf16 v[26:29], v[138:141], v[178:181], v[26:29]
	v_mfma_f32_16x16x32_bf16 v[14:17], v[130:133], v[186:189], v[14:17]
	v_mfma_f32_16x16x32_bf16 v[10:13], v[138:141], v[186:189], v[10:13]
	v_mfma_f32_16x16x32_bf16 v[62:65], v[134:137], v[166:169], v[62:65]
	v_mfma_f32_16x16x32_bf16 v[58:61], v[142:145], v[166:169], v[58:61]
	v_mfma_f32_16x16x32_bf16 v[46:49], v[134:137], v[174:177], v[46:49]
	v_mfma_f32_16x16x32_bf16 v[42:45], v[142:145], v[174:177], v[42:45]
	v_mfma_f32_16x16x32_bf16 v[30:33], v[134:137], v[182:185], v[30:33]
	v_mfma_f32_16x16x32_bf16 v[26:29], v[142:145], v[182:185], v[26:29]
	v_mfma_f32_16x16x32_bf16 v[14:17], v[134:137], v[190:193], v[14:17]
	v_mfma_f32_16x16x32_bf16 v[10:13], v[142:145], v[190:193], v[10:13]
	s_setprio 0
	s_setprio 1
	v_mfma_f32_16x16x32_bf16 v[54:57], v[146:149], v[162:165], v[54:57]
	v_mfma_f32_16x16x32_bf16 v[50:53], v[154:157], v[162:165], v[50:53]
	v_mfma_f32_16x16x32_bf16 v[38:41], v[146:149], v[170:173], v[38:41]
	v_mfma_f32_16x16x32_bf16 v[34:37], v[154:157], v[170:173], v[34:37]
	v_mfma_f32_16x16x32_bf16 v[22:25], v[146:149], v[178:181], v[22:25]
	v_mfma_f32_16x16x32_bf16 v[18:21], v[154:157], v[178:181], v[18:21]
	v_mfma_f32_16x16x32_bf16 v[6:9], v[146:149], v[186:189], v[6:9]
	v_mfma_f32_16x16x32_bf16 v[2:5], v[154:157], v[186:189], v[2:5]
	v_mfma_f32_16x16x32_bf16 v[54:57], v[150:153], v[166:169], v[54:57]
	v_mfma_f32_16x16x32_bf16 v[50:53], v[158:161], v[166:169], v[50:53]
	v_mfma_f32_16x16x32_bf16 v[38:41], v[150:153], v[174:177], v[38:41]
	v_mfma_f32_16x16x32_bf16 v[34:37], v[158:161], v[174:177], v[34:37]
	v_mfma_f32_16x16x32_bf16 v[22:25], v[150:153], v[182:185], v[22:25]
	v_mfma_f32_16x16x32_bf16 v[18:21], v[158:161], v[182:185], v[18:21]
	v_mfma_f32_16x16x32_bf16 v[6:9], v[150:153], v[190:193], v[6:9]
	v_mfma_f32_16x16x32_bf16 v[2:5], v[158:161], v[190:193], v[2:5]
	s_barrier
	s_setprio 0
	s_add_i32 s47, s47, 2
	s_add_u32 s90, s90, 0x1000
	s_addc_u32 s91, s91, 0
	s_add_u32 s37, s37, 0x100
	s_addc_u32 s46, s46, 0
	s_cmp_gt_u32 s47, 29
	s_cbranch_scc0 .LBB0_646
	s_and_b64 vcc, exec, s[14:15]
	s_cbranch_vccz .LBB0_649
	s_barrier
